# gMLP Y output (both tiles): 128x128-byte tile staged in free LDS and written as full 128-byte rows (2 x 16-byte stores per thread) instead of 8 x 4-byte pieces per lane; counted vmcnt waits re-derived
# speedup vs baseline: 1.0078x; 1.0078x over previous
; #define LAS __attribute__((address_space(3)))
; __device__ __forceinline__ bf16x8 pack8(f32x4 lo, f32x4 hi) { v4u w; w.x = pk2(lo[0], lo[1]); w.y = pk2(lo[2], lo[3]); w.z = pk2(hi[0], hi[1]); w.w = pk2(hi[2], hi[3]); return __builtin_bit_cast(bf16x8, w); }
; __device__ __forceinline__ void gmlp_compute(GmlpRegs& R, const Args& a, const Ctx& C, int c, int hd) {
;     ...
;     if (tid < 128) { const float mu = R.s1 * (1.0f / DA), var = R.s2 * (1.0f / DA) - mu * mu; ST[2 * tid] = mu; ST[2 * tid + 1] = __builtin_amdgcn_rsqf(var + EPS); }
;     __syncthreads();
;     const float lg = R.lg, lb = R.lb;
;     bf16x8 af[4];
; #pragma unroll
;     for (int ks = 0; ks < 4; ++ks) { f32x4 lo, hi;
; #pragma unroll
;         for (int e = 0; e < 8; ++e) { const int sl = 32 * ks + 8 * q + e;
;             const float v = __uint_as_float((unsigned)*(const LAS unsigned short*)(VL + sl * 260 + (16 * w + fr) * 2) << 16);
;             const float x = (v - ST[2 * sl]) * ST[2 * sl + 1] * lg + lb; if (e < 4) lo[e] = x; else hi[e - 4] = x; }
;         af[ks] = pack8(lo, hi); }
.LBB0_971:
	s_or_b64 exec, exec, s[76:77]
	v_or_b32_e32 v144, s2, v149
	v_lshrrev_b32_e32 v145, 4, v162
	v_lshl_add_u32 v165, v144, 1, 0
	s_movk_i32 s74, 0x820
	v_mad_u32_u24 v62, v145, s74, v165
	s_waitcnt lgkmcnt(0)
	s_barrier
	v_lshlrev_b32_e32 v63, 6, v145
	s_add_i32 s2, 0, 0x10a00
	v_add_u32_e32 v183, s2, v63
	v_lshlrev_b32_e32 v153, 3, v145
	v_or_b32_e32 v64, 2, v153
	s_waitcnt vmcnt(28)
	v_mov_b32_e32 v99, v98
	v_lshlrev_b32_e32 v52, 3, v64
	v_add_u32_e32 v168, s2, v52
	v_mov_b32_e32 v101, v100
	v_mul_u32_u24_e32 v167, 0x104, v64
	s_mov_b32 s74, 0x18000
	s_mov_b32 s75, 0x20000
	s_mov_b32 s76, 0x28000
	s_mov_b32 s77, 0x30000
	v_or_b32_e32 v52, 32, v63
	v_add_u32_e32 v163, s2, v52
	s_mov_b32 s78, 0x38000
	v_mul_u32_u24_e32 v184, 0x820, v145
	v_mul_u32_u24_e32 v200, 0x110, v149
	s_nop 0
	v_or_b32_e32 v52, 48, v63
	v_add_u32_e32 v166, s2, v52
	s_nop 0
	v_or_b32_e32 v54, 0x100, v63
	v_add_u32_e32 v185, s2, v54
	s_nop 0
	v_or_b32_e32 v54, 0x110, v63
	v_add_u32_e32 v186, s2, v54
	v_or_b32_e32 v65, 0x220, v63
	v_add_u32_e32 v192, s2, v65
	s_nop 0
	v_or_b32_e32 v54, 0x120, v63
	v_add_u32_e32 v188, s2, v54
	v_mov_b32_e32 v54, 0x2288
	v_mad_u32_u24 v54, v64, s33, v54
	v_add_u32_e32 v187, v165, v54
	s_nop 0
	v_or_b32_e32 v54, 0x130, v63
	v_add_u32_e32 v189, s2, v54
	v_or_b32_e32 v58, 0x200, v63
	v_add_u32_e32 v190, s2, v58
	v_or_b32_e32 v60, 0x210, v63
	v_add_u32_e32 v191, s2, v60
	v_or_b32_e32 v65, 0x230, v63
	v_add_u32_e32 v194, s2, v65
	v_mov_b32_e32 v65, 0x4510
	v_mad_u32_u24 v64, v64, s33, v65
	v_add_u32_e32 v193, v165, v64
	s_mov_b32 s33, 0x10000
	s_nop 0
	v_or_b32_e32 v64, 0x300, v63
	v_add_u32_e32 v195, s2, v64
	s_nop 0
	v_or_b32_e32 v64, 0x310, v63
	v_add_u32_e32 v196, s2, v64
	s_nop 0
	v_or_b32_e32 v64, 0x320, v63
	v_add_u32_e32 v197, s2, v64
	v_or_b32_e32 v63, 0x330, v63
	v_add_u32_e32 v198, s2, v63
	s_mov_b32 s2, 0x8000
	v_and_b32_e32 v66, 48, v0
	v_add_u32_e32 v199, 0, v66
	v_mad_u32_u24 v112, v149, s1, v199
	v_lshlrev_b32_e32 v82, 6, v145
	v_add_u32_e32 v82, 0x10a00, v82
	ds_read_u16 v66, v62 offset:34816
	ds_read_u16 v67, v62 offset:35076
	ds_read_u16 v68, v62 offset:35336
	ds_read_u16 v69, v62 offset:35596
	ds_read_u16 v70, v62 offset:35856
	ds_read_u16 v71, v62 offset:36116
	ds_read_u16 v72, v62 offset:36376
	ds_read_u16 v73, v62 offset:36636
	ds_read_b128 v[204:207], v82
	ds_read_b128 v[208:211], v82 offset:16
	ds_read_b128 v[212:215], v82 offset:32
	ds_read_b128 v[216:219], v82 offset:48
	ds_read_u16 v74, v62 offset:43136
	ds_read_u16 v75, v62 offset:43396
	ds_read_u16 v76, v62 offset:43656
	ds_read_u16 v77, v62 offset:43916
	ds_read_u16 v78, v62 offset:44176
	ds_read_u16 v79, v62 offset:44436
	ds_read_u16 v80, v62 offset:44696
	ds_read_u16 v81, v62 offset:44956
	ds_read_b128 v[220:223], v82 offset:256
	ds_read_b128 v[224:227], v82 offset:272
	ds_read_b128 v[228:231], v82 offset:288
	ds_read_b128 v[232:235], v82 offset:304
	s_waitcnt lgkmcnt(12)
	v_lshlrev_b32_e32 v66, 16, v66
	v_lshlrev_b32_e32 v67, 16, v67
	v_lshlrev_b32_e32 v68, 16, v68
	v_lshlrev_b32_e32 v69, 16, v69
	v_lshlrev_b32_e32 v70, 16, v70
	v_lshlrev_b32_e32 v71, 16, v71
	v_lshlrev_b32_e32 v72, 16, v72
	v_lshlrev_b32_e32 v73, 16, v73
	v_sub_f32_e32 v66, v66, v204
	v_sub_f32_e32 v67, v67, v206
	v_sub_f32_e32 v68, v68, v208
	v_sub_f32_e32 v69, v69, v210
	v_sub_f32_e32 v70, v70, v212
	v_sub_f32_e32 v71, v71, v214
	v_sub_f32_e32 v72, v72, v216
	v_sub_f32_e32 v73, v73, v218
	v_mul_f32_e32 v66, v205, v66
	v_mul_f32_e32 v67, v207, v67
	v_mul_f32_e32 v68, v209, v68
	v_mul_f32_e32 v69, v211, v69
	v_mul_f32_e32 v70, v213, v70
	v_mul_f32_e32 v71, v215, v71
	v_mul_f32_e32 v72, v217, v72
	v_mul_f32_e32 v73, v219, v73
	v_fma_f32 v66, v98, v66, v100
	v_fma_f32 v67, v98, v67, v100
	v_fma_f32 v68, v98, v68, v100
	v_fma_f32 v69, v98, v69, v100
	v_fma_f32 v70, v98, v70, v100
	v_fma_f32 v71, v98, v71, v100
	v_fma_f32 v72, v98, v72, v100
	v_fma_f32 v73, v98, v73, v100
	v_cvt_pk_bf16_f32 v50, v66, v67
	v_cvt_pk_bf16_f32 v51, v68, v69
	v_cvt_pk_bf16_f32 v52, v70, v71
	v_cvt_pk_bf16_f32 v53, v72, v73
	ds_read_u16 v66, v62 offset:51456
	ds_read_u16 v67, v62 offset:51716
	ds_read_u16 v68, v62 offset:51976
	ds_read_u16 v69, v62 offset:52236
	ds_read_u16 v70, v62 offset:52496
	ds_read_u16 v71, v62 offset:52756
	ds_read_u16 v72, v62 offset:53016
	ds_read_u16 v73, v62 offset:53276
	ds_read_b128 v[204:207], v82 offset:512
	ds_read_b128 v[208:211], v82 offset:528
	ds_read_b128 v[212:215], v82 offset:544
	ds_read_b128 v[216:219], v82 offset:560
	s_waitcnt lgkmcnt(12)
	v_lshlrev_b32_e32 v74, 16, v74
	v_lshlrev_b32_e32 v75, 16, v75
	v_lshlrev_b32_e32 v76, 16, v76
	v_lshlrev_b32_e32 v77, 16, v77
	v_lshlrev_b32_e32 v78, 16, v78
	v_lshlrev_b32_e32 v79, 16, v79
	v_lshlrev_b32_e32 v80, 16, v80
	v_lshlrev_b32_e32 v81, 16, v81
	v_sub_f32_e32 v74, v74, v220
	v_sub_f32_e32 v75, v75, v222
	v_sub_f32_e32 v76, v76, v224
	v_sub_f32_e32 v77, v77, v226
	v_sub_f32_e32 v78, v78, v228
	v_sub_f32_e32 v79, v79, v230
	v_sub_f32_e32 v80, v80, v232
	v_sub_f32_e32 v81, v81, v234
	v_mul_f32_e32 v74, v221, v74
	v_mul_f32_e32 v75, v223, v75
	v_mul_f32_e32 v76, v225, v76
	v_mul_f32_e32 v77, v227, v77
	v_mul_f32_e32 v78, v229, v78
	v_mul_f32_e32 v79, v231, v79
	v_mul_f32_e32 v80, v233, v80
	v_mul_f32_e32 v81, v235, v81
	v_fma_f32 v74, v98, v74, v100
	v_fma_f32 v75, v98, v75, v100
	v_fma_f32 v76, v98, v76, v100
	v_fma_f32 v77, v98, v77, v100
	v_fma_f32 v78, v98, v78, v100
	v_fma_f32 v79, v98, v79, v100
	v_fma_f32 v80, v98, v80, v100
	v_fma_f32 v81, v98, v81, v100
	v_cvt_pk_bf16_f32 v54, v74, v75
	v_cvt_pk_bf16_f32 v55, v76, v77
	v_cvt_pk_bf16_f32 v56, v78, v79
	v_cvt_pk_bf16_f32 v57, v80, v81
	ds_read_u16 v74, v62 offset:59776
	ds_read_u16 v75, v62 offset:60036
	ds_read_u16 v76, v62 offset:60296
	ds_read_u16 v77, v62 offset:60556
	ds_read_u16 v78, v62 offset:60816
	ds_read_u16 v79, v62 offset:61076
	ds_read_u16 v80, v62 offset:61336
	ds_read_u16 v81, v62 offset:61596
	ds_read_b128 v[220:223], v82 offset:768
	ds_read_b128 v[224:227], v82 offset:784
	ds_read_b128 v[228:231], v82 offset:800
	ds_read_b128 v[232:235], v82 offset:816
	s_waitcnt lgkmcnt(12)
; #define LAS __attribute__((address_space(3)))
; #define MFMA16(A, B, Cc) __builtin_amdgcn_mfma_f32_16x16x32_bf16((A), (B), (Cc), 0, 0, 0)
; #define PIN(x) asm volatile("" : "+v"(x))
; __device__ __forceinline__ float bf_lo(unsigned w) { return __uint_as_float(w << 16); }
; __device__ __forceinline__ unsigned pk4f8(float a, float b, float c, float d) { int p = __builtin_amdgcn_cvt_pk_fp8_f32(sat8(a), sat8(b), 0, false); p = __builtin_amdgcn_cvt_pk_fp8_f32(sat8(c), sat8(d), p, true); return (unsigned)p; }
; __device__ __forceinline__ float bf_hi(unsigned w) { return __uint_as_float(w & 0xffff0000u); }
; __device__ __forceinline__ bf16x8 pack8(f32x4 lo, f32x4 hi) { v4u w; w.x = pk2(lo[0], lo[1]); w.y = pk2(lo[2], lo[3]); w.z = pk2(hi[0], hi[1]); w.w = pk2(hi[2], hi[3]); return __builtin_bit_cast(bf16x8, w); }
; __device__ __forceinline__ void gmlp_compute(GmlpRegs& R, const Args& a, const Ctx& C, int c, int hd) {
;     ...
;         for (int e = 0; e < 8; ++e) { const int sl = 32 * ks + 8 * q + e;
;             const float v = __uint_as_float((unsigned)*(const LAS unsigned short*)(VL + sl * 260 + (16 * w + fr) * 2) << 16);
;             const float x = (v - ST[2 * sl]) * ST[2 * sl + 1] * lg + lb; if (e < 4) lo[e] = x; else hi[e - 4] = x; }
;         af[ks] = pack8(lo, hi); }
;     f32x4 acc[8];
; #pragma unroll
;     for (int nt = 0; nt < 8; ++nt) { acc[nt] = (f32x4){0.f, 0.f, 0.f, 0.f};
; #pragma unroll
;         for (int ks = 0; ks <= nt / 2; ++ks) acc[nt] = MFMA16(af[ks], *(const LAS bf16x8*)(WL + (16 * nt + fr) * 272 + (32 * ks + 8 * q) * 2), acc[nt]); }
; #pragma unroll
;     for (int nt = 0; nt < 8; ++nt) PIN(R.uq[nt]);
; #pragma unroll
;     for (int nt = 0; nt < 8; ++nt) { const size_t row = T0 + 16 * nt + fr; const float bs = R.bsv[nt];
;         const float o0 = bf_lo(R.uq[nt].x) * (acc[nt][0] + bs), o1 = bf_hi(R.uq[nt].x) * (acc[nt][1] + bs);
;         const float o2 = bf_lo(R.uq[nt].y) * (acc[nt][2] + bs), o3 = bf_hi(R.uq[nt].y) * (acc[nt][3] + bs);
;         *(unsigned*)((unsigned char*)Y + row * DM + chs) = pk4f8(o0, o1, o2, o3); }
	v_lshlrev_b32_e32 v66, 16, v66
	v_lshlrev_b32_e32 v67, 16, v67
	v_lshlrev_b32_e32 v68, 16, v68
	v_lshlrev_b32_e32 v69, 16, v69
	v_lshlrev_b32_e32 v70, 16, v70
	v_lshlrev_b32_e32 v71, 16, v71
	v_lshlrev_b32_e32 v72, 16, v72
	v_lshlrev_b32_e32 v73, 16, v73
	v_sub_f32_e32 v66, v66, v204
	v_sub_f32_e32 v67, v67, v206
	v_sub_f32_e32 v68, v68, v208
	v_sub_f32_e32 v69, v69, v210
	v_sub_f32_e32 v70, v70, v212
	v_sub_f32_e32 v71, v71, v214
	v_sub_f32_e32 v72, v72, v216
	v_sub_f32_e32 v73, v73, v218
	v_mul_f32_e32 v66, v205, v66
	v_mul_f32_e32 v67, v207, v67
	v_mul_f32_e32 v68, v209, v68
	v_mul_f32_e32 v69, v211, v69
	v_mul_f32_e32 v70, v213, v70
	v_mul_f32_e32 v71, v215, v71
	v_mul_f32_e32 v72, v217, v72
	v_mul_f32_e32 v73, v219, v73
	v_fma_f32 v66, v98, v66, v100
	v_fma_f32 v67, v98, v67, v100
	v_fma_f32 v68, v98, v68, v100
	v_fma_f32 v69, v98, v69, v100
	v_fma_f32 v70, v98, v70, v100
	v_fma_f32 v71, v98, v71, v100
	v_fma_f32 v72, v98, v72, v100
	v_fma_f32 v73, v98, v73, v100
	v_cvt_pk_bf16_f32 v58, v66, v67
	v_cvt_pk_bf16_f32 v59, v68, v69
	v_cvt_pk_bf16_f32 v60, v70, v71
	v_cvt_pk_bf16_f32 v61, v72, v73
	s_waitcnt lgkmcnt(0)
	v_lshlrev_b32_e32 v74, 16, v74
	v_lshlrev_b32_e32 v75, 16, v75
	v_lshlrev_b32_e32 v76, 16, v76
	v_lshlrev_b32_e32 v77, 16, v77
	v_lshlrev_b32_e32 v78, 16, v78
	v_lshlrev_b32_e32 v79, 16, v79
	v_lshlrev_b32_e32 v80, 16, v80
	v_lshlrev_b32_e32 v81, 16, v81
	v_sub_f32_e32 v74, v74, v220
	v_sub_f32_e32 v75, v75, v222
	v_sub_f32_e32 v76, v76, v224
	v_sub_f32_e32 v77, v77, v226
	v_sub_f32_e32 v78, v78, v228
	v_sub_f32_e32 v79, v79, v230
	v_sub_f32_e32 v80, v80, v232
	v_sub_f32_e32 v81, v81, v234
	v_mul_f32_e32 v74, v221, v74
	v_mul_f32_e32 v75, v223, v75
	v_mul_f32_e32 v76, v225, v76
	v_mul_f32_e32 v77, v227, v77
	v_mul_f32_e32 v78, v229, v78
	v_mul_f32_e32 v79, v231, v79
	v_mul_f32_e32 v80, v233, v80
	v_mul_f32_e32 v81, v235, v81
	v_fma_f32 v74, v98, v74, v100
	v_fma_f32 v75, v98, v75, v100
	v_fma_f32 v76, v98, v76, v100
	v_fma_f32 v77, v98, v77, v100
	v_fma_f32 v78, v98, v78, v100
	v_fma_f32 v79, v98, v79, v100
	v_fma_f32 v80, v98, v80, v100
	v_fma_f32 v81, v98, v81, v100
	v_cvt_pk_bf16_f32 v62, v74, v75
	v_cvt_pk_bf16_f32 v63, v76, v77
	v_cvt_pk_bf16_f32 v64, v78, v79
	v_cvt_pk_bf16_f32 v65, v80, v81
	ds_read_b128 v[66:69], v112
	ds_read_b128 v[70:73], v112 offset:8704
	s_waitcnt lgkmcnt(1)
	v_mfma_f32_16x16x32_bf16 v[78:81], v[50:53], v[66:69], 0
	ds_read_b128 v[66:69], v112 offset:4352
	ds_read_b128 v[74:77], v112 offset:8768
	ds_read_b128 v[82:85], v112 offset:13120
	s_waitcnt lgkmcnt(3)
	v_mfma_f32_16x16x32_bf16 v[70:73], v[50:53], v[70:73], 0
	ds_read_b128 v[86:89], v112 offset:17472
	ds_read_b128 v[90:93], v112 offset:21824
	ds_read_b128 v[202:205], v112 offset:26176
	s_waitcnt lgkmcnt(4)
	v_mfma_f32_16x16x32_bf16 v[70:73], v[54:57], v[74:77], v[70:73]
	ds_read_b128 v[74:77], v112 offset:13056
	s_mov_b32 s1, 0xc3e00000
	s_waitcnt lgkmcnt(0)
	v_mfma_f32_16x16x32_bf16 v[74:77], v[50:53], v[74:77], 0
	v_mfma_f32_16x16x32_bf16 v[74:77], v[54:57], v[82:85], v[74:77]
	ds_read_b128 v[82:85], v112 offset:17408
	s_waitcnt lgkmcnt(0)
	v_mfma_f32_16x16x32_bf16 v[82:85], v[50:53], v[82:85], 0
	v_mfma_f32_16x16x32_bf16 v[82:85], v[54:57], v[86:89], v[82:85]
	ds_read_b128 v[86:89], v112 offset:17536
	s_waitcnt lgkmcnt(0)
	v_mfma_f32_16x16x32_bf16 v[82:85], v[58:61], v[86:89], v[82:85]
	ds_read_b128 v[86:89], v112 offset:21760
	s_waitcnt lgkmcnt(0)
	v_mfma_f32_16x16x32_bf16 v[86:89], v[50:53], v[86:89], 0
	v_mfma_f32_16x16x32_bf16 v[86:89], v[54:57], v[90:93], v[86:89]
	ds_read_b128 v[90:93], v112 offset:21888
	s_waitcnt lgkmcnt(0)
	v_mfma_f32_16x16x32_bf16 v[86:89], v[58:61], v[90:93], v[86:89]
	ds_read_b128 v[90:93], v112 offset:26112
	s_waitcnt lgkmcnt(0)
	v_mfma_f32_16x16x32_bf16 v[90:93], v[50:53], v[90:93], 0
	v_mfma_f32_16x16x32_bf16 v[90:93], v[54:57], v[202:205], v[90:93]
	ds_read_b128 v[202:205], v112 offset:26240
	s_waitcnt lgkmcnt(0)
	v_mfma_f32_16x16x32_bf16 v[90:93], v[58:61], v[202:205], v[90:93]
	ds_read_b128 v[202:205], v112 offset:26304
	s_waitcnt lgkmcnt(0)
	v_mfma_f32_16x16x32_bf16 v[90:93], v[62:65], v[202:205], v[90:93]
	ds_read_b128 v[202:205], v112 offset:30464
	v_mfma_f32_16x16x32_bf16 v[66:69], v[50:53], v[66:69], 0
	s_waitcnt lgkmcnt(0)
	v_mfma_f32_16x16x32_bf16 v[50:53], v[50:53], v[202:205], 0
	ds_read_b128 v[202:205], v112 offset:30528
	s_waitcnt lgkmcnt(0)
	v_mfma_f32_16x16x32_bf16 v[50:53], v[54:57], v[202:205], v[50:53]
	ds_read_b128 v[54:57], v112 offset:30592
	s_waitcnt lgkmcnt(0)
	v_mfma_f32_16x16x32_bf16 v[50:53], v[58:61], v[54:57], v[50:53]
	ds_read_b128 v[54:57], v112 offset:30656
	s_waitcnt vmcnt(27)
	v_lshlrev_b32_e32 v112, 2, v145
	s_waitcnt lgkmcnt(0)
	v_mfma_f32_16x16x32_bf16 v[50:53], v[62:65], v[54:57], v[50:53]
	v_lshlrev_b32_e32 v54, 16, v140
	s_waitcnt vmcnt(19)
	v_add_f32_e32 v55, v161, v78
	v_mul_f32_e32 v54, v55, v54
	v_and_b32_e32 v55, 0xffff0000, v140
	v_add_f32_e32 v56, v161, v79
	v_or_b32_e32 v128, s0, v112
	v_mul_f32_e32 v55, v56, v55
	v_lshlrev_b32_e32 v56, 16, v141
	v_add_f32_e32 v57, v161, v80
	v_lshl_add_u64 v[142:143], s[70:71], 0, v[128:129]
	v_and_b32_e32 v204, 0xffffff80, v128
	v_and_b32_e32 v206, 0x7f, v128
	v_mov_b32_e32 v205, 0
	v_lshl_add_u64 v[202:203], s[70:71], 0, v[204:205]
	v_mov_b32_e32 v228, v202
	v_mov_b32_e32 v229, v203
	v_and_b32_e32 v230, 0x7f, v128
	v_mul_f32_e32 v56, v57, v56
	v_and_b32_e32 v57, 0xffff0000, v141
	v_add_f32_e32 v58, v161, v81
	v_mov_b32_e32 v128, 0x43e00000
	v_mul_f32_e32 v57, v58, v57
	v_med3_f32 v54, v54, s1, v128
	v_med3_f32 v55, v55, s1, v128
	v_mov_b32_e32 v58, v129
	v_cvt_pk_fp8_f32 v58, v54, v55
	v_med3_f32 v54, v56, s1, v128
	v_med3_f32 v55, v57, s1, v128
	v_cvt_pk_fp8_f32 v58, v54, v55 op_sel:[0,0,1]
	v_lshlrev_b64 v[54:55], 11, v[136:137]
	v_and_b32_e32 v207, 0x7f, v136
	v_and_b32_e32 v201, 0xffffff80, v136
	s_movk_i32 s32, 0x90
	v_mad_u32_u24 v206, v207, s32, v206
	v_add_u32_e32 v206, 0x12000, v206
	v_lshl_add_u64 v[54:55], v[142:143], 0, v[54:55]
	v_lshlrev_b32_e32 v56, 16, v138
	s_waitcnt vmcnt(18)
; __device__ __forceinline__ float bf_lo(unsigned w) { return __uint_as_float(w << 16); }
; __device__ __forceinline__ unsigned pk4f8(float a, float b, float c, float d) { int p = __builtin_amdgcn_cvt_pk_fp8_f32(sat8(a), sat8(b), 0, false); p = __builtin_amdgcn_cvt_pk_fp8_f32(sat8(c), sat8(d), p, true); return (unsigned)p; }
; __device__ __forceinline__ float bf_hi(unsigned w) { return __uint_as_float(w & 0xffff0000u); }
; __device__ __forceinline__ void gmlp_compute(GmlpRegs& R, const Args& a, const Ctx& C, int c, int hd) {
;     ...
;     for (int nt = 0; nt < 8; ++nt) { const size_t row = T0 + 16 * nt + fr; const float bs = R.bsv[nt];
;         const float o0 = bf_lo(R.uq[nt].x) * (acc[nt][0] + bs), o1 = bf_hi(R.uq[nt].x) * (acc[nt][1] + bs);
;         const float o2 = bf_lo(R.uq[nt].y) * (acc[nt][2] + bs), o3 = bf_hi(R.uq[nt].y) * (acc[nt][3] + bs);
;         *(unsigned*)((unsigned char*)Y + row * DM + chs) = pk4f8(o0, o1, o2, o3); }
	v_add_f32_e32 v57, v160, v66
	ds_write_b32 v206, v58
	v_mul_f32_e32 v56, v57, v56
	v_and_b32_e32 v57, 0xffff0000, v138
	v_add_f32_e32 v58, v160, v67
	v_mul_f32_e32 v57, v58, v57
	v_lshlrev_b32_e32 v58, 16, v139
	v_add_f32_e32 v59, v160, v68
	v_mul_f32_e32 v58, v59, v58
	v_and_b32_e32 v59, 0xffff0000, v139
	v_add_f32_e32 v60, v160, v69
	v_mul_f32_e32 v59, v60, v59
	v_med3_f32 v56, v56, s1, v128
	v_med3_f32 v57, v57, s1, v128
	v_mov_b32_e32 v60, v129
	v_cvt_pk_fp8_f32 v60, v56, v57
	v_med3_f32 v56, v58, s1, v128
	v_med3_f32 v57, v59, s1, v128
	s_waitcnt vmcnt(17)
	v_add_f32_e32 v58, v159, v71
	v_cvt_pk_fp8_f32 v60, v56, v57 op_sel:[0,0,1]
	v_add_co_u32_e64 v56, s[70:71], s2, v54
	v_add_f32_e32 v59, v159, v72
	s_nop 0
	v_addc_co_u32_e64 v57, s[70:71], 0, v55, s[70:71]
	ds_write_b32 v206, v60 offset:2304
	v_lshlrev_b32_e32 v56, 16, v134
	v_add_f32_e32 v57, v159, v70
	v_mul_f32_e32 v56, v57, v56
	v_and_b32_e32 v57, 0xffff0000, v134
	v_mul_f32_e32 v57, v58, v57
	v_lshlrev_b32_e32 v58, 16, v135
	v_mul_f32_e32 v58, v59, v58
	v_and_b32_e32 v59, 0xffff0000, v135
	v_add_f32_e32 v60, v159, v73
	v_mul_f32_e32 v59, v60, v59
	v_med3_f32 v56, v56, s1, v128
	v_med3_f32 v57, v57, s1, v128
	v_mov_b32_e32 v60, v129
	v_cvt_pk_fp8_f32 v60, v56, v57
	v_med3_f32 v56, v58, s1, v128
	v_med3_f32 v57, v59, s1, v128
	s_waitcnt vmcnt(16)
	v_add_f32_e32 v58, v156, v75
	v_cvt_pk_fp8_f32 v60, v56, v57 op_sel:[0,0,1]
	v_add_co_u32_e64 v56, s[70:71], s33, v54
	v_add_f32_e32 v59, v156, v76
	s_nop 0
	v_addc_co_u32_e64 v57, s[70:71], 0, v55, s[70:71]
	ds_write_b32 v206, v60 offset:4608
	v_lshlrev_b32_e32 v56, 16, v132
	v_add_f32_e32 v57, v156, v74
	v_mul_f32_e32 v56, v57, v56
	v_and_b32_e32 v57, 0xffff0000, v132
	v_mul_f32_e32 v57, v58, v57
	v_lshlrev_b32_e32 v58, 16, v133
	v_mul_f32_e32 v58, v59, v58
	v_and_b32_e32 v59, 0xffff0000, v133
	v_add_f32_e32 v60, v156, v77
	v_mul_f32_e32 v59, v60, v59
	v_med3_f32 v56, v56, s1, v128
	v_med3_f32 v57, v57, s1, v128
	v_mov_b32_e32 v60, v129
	v_cvt_pk_fp8_f32 v60, v56, v57
	v_med3_f32 v56, v58, s1, v128
	v_med3_f32 v57, v59, s1, v128
	s_waitcnt vmcnt(15)
	v_add_f32_e32 v58, v154, v83
	v_cvt_pk_fp8_f32 v60, v56, v57 op_sel:[0,0,1]
	v_add_co_u32_e64 v56, s[70:71], s74, v54
	v_add_f32_e32 v59, v154, v84
	s_nop 0
	v_addc_co_u32_e64 v57, s[70:71], 0, v55, s[70:71]
	ds_write_b32 v206, v60 offset:6912
	v_lshlrev_b32_e32 v56, 16, v130
	v_add_f32_e32 v57, v154, v82
	v_mul_f32_e32 v56, v57, v56
	v_and_b32_e32 v57, 0xffff0000, v130
	v_mul_f32_e32 v57, v58, v57
	v_lshlrev_b32_e32 v58, 16, v131
	v_mul_f32_e32 v58, v59, v58
	v_and_b32_e32 v59, 0xffff0000, v131
	v_add_f32_e32 v60, v154, v85
	v_mul_f32_e32 v59, v60, v59
	v_med3_f32 v56, v56, s1, v128
	v_med3_f32 v57, v57, s1, v128
	v_mov_b32_e32 v60, v129
	v_cvt_pk_fp8_f32 v60, v56, v57
	v_med3_f32 v56, v58, s1, v128
	v_med3_f32 v57, v59, s1, v128
	s_waitcnt vmcnt(14)
	v_add_f32_e32 v58, v152, v87
	v_cvt_pk_fp8_f32 v60, v56, v57 op_sel:[0,0,1]
	v_add_co_u32_e64 v56, s[70:71], s75, v54
	v_add_f32_e32 v59, v152, v88
	s_nop 0
	v_addc_co_u32_e64 v57, s[70:71], 0, v55, s[70:71]
	ds_write_b32 v206, v60 offset:9216
	v_lshlrev_b32_e32 v56, 16, v126
	v_add_f32_e32 v57, v152, v86
	v_mul_f32_e32 v56, v57, v56
	v_and_b32_e32 v57, 0xffff0000, v126
	v_mul_f32_e32 v57, v58, v57
	v_lshlrev_b32_e32 v58, 16, v127
	v_mul_f32_e32 v58, v59, v58
	v_and_b32_e32 v59, 0xffff0000, v127
	v_add_f32_e32 v60, v152, v89
	v_mul_f32_e32 v59, v60, v59
	v_med3_f32 v56, v56, s1, v128
	v_med3_f32 v57, v57, s1, v128
	v_mov_b32_e32 v60, v129
	v_cvt_pk_fp8_f32 v60, v56, v57
	v_med3_f32 v56, v58, s1, v128
	v_med3_f32 v57, v59, s1, v128
	s_waitcnt vmcnt(13)
	v_add_f32_e32 v58, v151, v91
	v_cvt_pk_fp8_f32 v60, v56, v57 op_sel:[0,0,1]
	v_add_co_u32_e64 v56, s[70:71], s76, v54
	v_add_f32_e32 v59, v151, v92
	s_nop 0
	v_addc_co_u32_e64 v57, s[70:71], 0, v55, s[70:71]
	ds_write_b32 v206, v60 offset:11520
	v_lshlrev_b32_e32 v56, 16, v124
	v_add_f32_e32 v57, v151, v90
	v_mul_f32_e32 v56, v57, v56
	v_and_b32_e32 v57, 0xffff0000, v124
	v_mul_f32_e32 v57, v58, v57
	v_lshlrev_b32_e32 v58, 16, v125
	v_mul_f32_e32 v58, v59, v58
	v_and_b32_e32 v59, 0xffff0000, v125
	v_add_f32_e32 v60, v151, v93
	v_mul_f32_e32 v59, v60, v59
	v_med3_f32 v56, v56, s1, v128
	v_med3_f32 v57, v57, s1, v128
	v_mov_b32_e32 v60, v129
	v_cvt_pk_fp8_f32 v60, v56, v57
	v_med3_f32 v56, v58, s1, v128
	v_med3_f32 v57, v59, s1, v128
	s_waitcnt vmcnt(12)
	v_add_f32_e32 v50, v150, v50
	v_cvt_pk_fp8_f32 v60, v56, v57 op_sel:[0,0,1]
	v_add_co_u32_e64 v56, s[70:71], s77, v54
	v_add_f32_e32 v51, v150, v51
	s_nop 0
	v_addc_co_u32_e64 v57, s[70:71], 0, v55, s[70:71]
	ds_write_b32 v206, v60 offset:13824
	v_lshlrev_b32_e32 v56, 16, v122
	v_mul_f32_e32 v50, v50, v56
	v_and_b32_e32 v56, 0xffff0000, v122
	v_mul_f32_e32 v51, v51, v56
	v_med3_f32 v50, v50, s1, v128
	v_med3_f32 v51, v51, s1, v128
	v_lshlrev_b32_e32 v56, 16, v123
	v_add_f32_e32 v52, v150, v52
	v_cvt_pk_fp8_f32 v129, v50, v51
	v_mul_f32_e32 v52, v52, v56
	v_and_b32_e32 v56, 0xffff0000, v123
	v_add_f32_e32 v53, v150, v53
	v_mul_f32_e32 v53, v53, v56
	v_med3_f32 v50, v52, s1, v128
	v_med3_f32 v51, v53, s1, v128
	v_cvt_pk_fp8_f32 v129, v50, v51 op_sel:[0,0,1]
	v_add_co_u32_e64 v50, s[70:71], s78, v54
	v_readlane_b32 s0, v249, 0
	s_nop 0
	v_addc_co_u32_e64 v51, s[70:71], 0, v55, s[70:71]
	s_ashr_i32 s70, s0, 6
	s_ashr_i32 s71, s70, 31
	s_and_b32 s0, s0, 63
	s_lshl_b64 s[80:81], s[70:71], 16
	s_add_u32 s79, s94, s80
	s_addc_u32 s80, s95, s81
	s_mul_i32 s81, s0, 0x42000
	s_add_u32 s79, s79, s81
	s_addc_u32 s81, s80, 0
	s_add_u32 s80, s79, 0xc200000
	ds_write_b32 v206, v129 offset:16128
	s_waitcnt lgkmcnt(0)
	s_barrier
; #define LAS __attribute__((address_space(3)))
; __device__ __forceinline__ unsigned pk2(float lo, float hi) { return pg8::cvt_pk_bf16(lo, hi); }
; __device__ __forceinline__ void s5_xs_load(v4u (&xv)[8], const Args& a, const Ctx& C, int b, int g) {
;     const bf16* XBg = (const bf16*)(a.ws + WS_XB) + ((size_t)g * MP + (size_t)b * SEQ) * 16;
; #pragma unroll
;     for (int i = 0; i < 8; ++i) xv[i] = __builtin_nontemporal_load((const v4u*)(XBg + (size_t)(C.tid + 512 * i) * 8));
; }
; __device__ __forceinline__ void gmlp_compute(GmlpRegs& R, const Args& a, const Ctx& C, int c, int hd) {
;     ...
;     __syncthreads();
; #pragma unroll
;     for (int i = 0; i < 8; ++i) { const int idx = tid + 512 * i, tr = idx >> 5, c4 = (idx & 31) * 4; f32x4 x = R.wv[i];
; #pragma unroll
;         for (int j = 0; j < 4; ++j) x[j] = (c4 + j <= tr) ? x[j] : 0.f;
;         *(LAS v2u*)(WL + tr * 272 + c4 * 2) = (v2u){pk2(x[0], x[1]), pk2(x[2], x[3])}; }
; #pragma unroll
;     for (int i = 0; i < 4; ++i) { const int idx = tid + 512 * i; LAS unsigned* d = (LAS unsigned*)(VL + (idx >> 4) * 260 + (idx & 15) * 16); d[0] = R.vv[i].x; d[1] = R.vv[i].y; d[2] = R.vv[i].z; d[3] = R.vv[i].w; }
;     if (tid < 128) { const float mu = R.s1 * (1.0f / DA), var = R.s2 * (1.0f / DA) - mu * mu; ST[2 * tid] = mu; ST[2 * tid + 1] = __builtin_amdgcn_rsqf(var + EPS); }
	v_lshrrev_b32_e32 v214, 3, v0
	v_and_b32_e32 v218, 7, v0
	v_lshlrev_b32_e32 v218, 4, v218
	s_movk_i32 s32, 0x90
	v_mad_u32_u24 v220, v214, s32, v218
	v_add_u32_e32 v220, 0x12000, v220
	ds_read_b128 v[208:211], v220
	ds_read_b128 v[222:225], v220 offset:9216
	v_add_u32_e32 v214, v201, v214
	v_mov_b32_e32 v215, 0
	v_mov_b32_e32 v219, 0
	v_lshlrev_b64 v[216:217], 11, v[214:215]
	v_lshl_add_u64 v[216:217], v[202:203], 0, v[216:217]
	v_lshl_add_u64 v[216:217], v[216:217], 0, v[218:219]
	v_mov_b32_e32 v218, 0x20000
	v_lshl_add_u64 v[226:227], v[216:217], 0, v[218:219]
	s_waitcnt lgkmcnt(0)
	global_store_dwordx4 v[216:217], v[208:211], off
	global_store_dwordx4 v[226:227], v[222:225], off
	s_addc_u32 s81, s81, 0
	v_lshlrev_b32_e32 v87, 4, v146
	v_lshlrev_b32_e32 v86, 4, v95
	v_lshlrev_b32_e32 v85, 4, v120
	v_lshlrev_b32_e32 v84, 4, v157
	v_lshlrev_b32_e32 v83, 4, v158
	v_lshlrev_b32_e32 v82, 4, v155
	global_load_dwordx4 v[74:77], v94, s[80:81] nt
	global_load_dwordx4 v[78:81], v87, s[80:81] nt
	global_load_dwordx4 v[70:73], v148, s[80:81] nt
	global_load_dwordx4 v[66:69], v86, s[80:81] nt
	global_load_dwordx4 v[58:61], v85, s[80:81] nt
	global_load_dwordx4 v[62:65], v84, s[80:81] nt
	global_load_dwordx4 v[50:53], v83, s[80:81] nt
	global_load_dwordx4 v[54:57], v82, s[80:81] nt
	s_nop 0
	v_cndmask_b32_e64 v26, v26, 0, s[68:69]
	v_cndmask_b32_e64 v27, 0, v27, s[4:5]
	v_cndmask_b32_e64 v28, v28, 0, s[6:7]
	v_cndmask_b32_e64 v29, v29, 0, s[8:9]
	v_cvt_pk_bf16_f32 v26, v26, v27
	v_cvt_pk_bf16_f32 v27, v28, v29
	v_add_u32_e32 v28, v164, v169
	s_waitcnt vmcnt(21)
	s_waitcnt vmcnt(20)
	s_waitcnt vmcnt(19)
	s_waitcnt vmcnt(18)
	s_barrier
	ds_write_b64 v28, v[26:27]
	v_cndmask_b32_e64 v26, v30, 0, s[10:11]
	v_cndmask_b32_e64 v27, 0, v31, s[14:15]
	v_cndmask_b32_e64 v28, v32, 0, s[16:17]
	v_cndmask_b32_e64 v29, v33, 0, s[18:19]
	v_cndmask_b32_e64 v18, v18, 0, s[20:21]
	v_cndmask_b32_e64 v19, 0, v19, s[22:23]
	v_cndmask_b32_e64 v20, v20, 0, s[24:25]
	v_cndmask_b32_e64 v21, v21, 0, s[26:27]
	v_cvt_pk_bf16_f32 v26, v26, v27
	v_cvt_pk_bf16_f32 v27, v28, v29
	v_add_u32_e32 v28, v164, v170
	v_cvt_pk_bf16_f32 v18, v18, v19
	v_cvt_pk_bf16_f32 v19, v20, v21
	v_add_u32_e32 v20, v164, v171
	ds_write_b64 v28, v[26:27]
	ds_write_b64 v20, v[18:19]
	v_cndmask_b32_e64 v18, v22, 0, s[72:73]
	v_cndmask_b32_e64 v19, 0, v23, s[28:29]
	v_cndmask_b32_e64 v20, v24, 0, s[30:31]
	v_cndmask_b32_e64 v21, v25, 0, s[34:35]
	v_cndmask_b32_e64 v10, v10, 0, s[36:37]
	v_cndmask_b32_e64 v11, 0, v11, s[38:39]
	v_cndmask_b32_e64 v12, v12, 0, s[40:41]
	v_cndmask_b32_e64 v13, v13, 0, s[42:43]
	v_cvt_pk_bf16_f32 v18, v18, v19
	v_cvt_pk_bf16_f32 v19, v20, v21
	v_add_u32_e32 v20, v164, v172
	v_cvt_pk_bf16_f32 v10, v10, v11
	v_cvt_pk_bf16_f32 v11, v12, v13
	v_add_u32_e32 v12, v164, v173
	ds_write_b64 v20, v[18:19]
	ds_write_b64 v12, v[10:11]
	v_cndmask_b32_e64 v10, v14, 0, s[44:45]
	v_cndmask_b32_e64 v11, 0, v15, s[46:47]
	v_cndmask_b32_e64 v12, v16, 0, s[48:49]
	v_cndmask_b32_e64 v13, v17, 0, s[50:51]
	v_cndmask_b32_e64 v6, v6, 0, s[52:53]
	v_cndmask_b32_e64 v7, 0, v7, s[54:55]
	v_cndmask_b32_e64 v8, v8, 0, s[56:57]
	v_cndmask_b32_e64 v9, v9, 0, s[58:59]
	v_cndmask_b32_e64 v2, v2, 0, s[60:61]
	v_cndmask_b32_e64 v3, 0, v3, s[62:63]
	v_cndmask_b32_e64 v4, v4, 0, s[64:65]
	v_cndmask_b32_e64 v5, v5, 0, s[66:67]
	v_cvt_pk_bf16_f32 v10, v10, v11
	v_cvt_pk_bf16_f32 v11, v12, v13
	v_add_u32_e32 v12, v164, v174
	v_cvt_pk_bf16_f32 v6, v6, v7
	v_cvt_pk_bf16_f32 v7, v8, v9
	v_add_u32_e32 v8, v164, v176
	v_cvt_pk_bf16_f32 v2, v2, v3
	v_cvt_pk_bf16_f32 v3, v4, v5
	v_add_u32_e32 v4, v164, v178
	ds_write_b64 v12, v[10:11]
	ds_write_b64 v8, v[6:7]
	ds_write_b64 v4, v[2:3]
	v_add_u32_e32 v2, v175, v179
	v_add_u32_e32 v3, 0x8800, v2
	v_add_u32_e32 v2, 0x8808, v2
	ds_write2_b32 v2, v40, v41 offset1:1
	v_add_u32_e32 v2, v175, v180
	ds_write2_b32 v3, v38, v39 offset1:1
	v_add_u32_e32 v3, 0x8800, v2
	v_add_u32_e32 v2, 0x8808, v2
	ds_write2_b32 v2, v36, v37 offset1:1
	v_add_u32_e32 v2, v175, v181
	ds_write2_b32 v3, v34, v35 offset1:1
	v_add_u32_e32 v3, 0x8800, v2
	v_add_u32_e32 v2, 0x8808, v2
	ds_write2_b32 v2, v48, v49 offset1:1
	v_add_u32_e32 v2, v175, v182
	ds_write2_b32 v3, v46, v47 offset1:1
	v_add_u32_e32 v3, 0x8800, v2
	v_add_u32_e32 v2, 0x8808, v2
	ds_write2_b32 v3, v42, v43 offset1:1
	ds_write2_b32 v2, v44, v45 offset1:1
	s_and_saveexec_b64 s[4:5], vcc
	s_cbranch_execz .LBB0_973
	s_waitcnt vmcnt(18)
	v_mul_f32_e32 v113, 0x3a800000, v252
	v_mul_f32_e32 v121, 0x3a800000, v253
	v_fma_f32 v2, -v121, v121, v113
	v_add_f32_e32 v2, 0x358637bd, v2
	v_rsq_f32_e32 v3, v2
	v_add_u32_e32 v4, 0x10a00, v177
	v_mov_b32_e32 v2, v121
	ds_write_b64 v4, v[2:3]
; #define LAS __attribute__((address_space(3)))
; __device__ __forceinline__ bf16x8 pack8(f32x4 lo, f32x4 hi) { v4u w; w.x = pk2(lo[0], lo[1]); w.y = pk2(lo[2], lo[3]); w.z = pk2(hi[0], hi[1]); w.w = pk2(hi[2], hi[3]); return __builtin_bit_cast(bf16x8, w); }
; __device__ __forceinline__ void gmlp_compute(GmlpRegs& R, const Args& a, const Ctx& C, int c, int hd) {
;     ...
;     const float lg = R.lg, lb = R.lb;
;     bf16x8 af[4];
; #pragma unroll
;     for (int ks = 0; ks < 4; ++ks) { f32x4 lo, hi;
; #pragma unroll
;         for (int e = 0; e < 8; ++e) { const int sl = 32 * ks + 8 * q + e;
;             const float v = __uint_as_float((unsigned)*(const LAS unsigned short*)(VL + sl * 260 + (16 * w + fr) * 2) << 16);
;             const float x = (v - ST[2 * sl]) * ST[2 * sl + 1] * lg + lb; if (e < 4) lo[e] = x; else hi[e - 4] = x; }
;         af[ks] = pack8(lo, hi); }
.LBB0_973:
	s_or_b64 exec, exec, s[4:5]
	s_waitcnt lgkmcnt(0)
	s_barrier
	v_add_u32_e32 v18, v165, v184
	ds_read_b128 v[2:5], v183
	ds_read_u16 v6, v18 offset:34816
	ds_read_u16 v7, v18 offset:35076
	ds_read_u16 v14, v18 offset:35596
	ds_read_u16 v15, v18 offset:36116
	ds_read_u16 v19, v18 offset:36636
	ds_read_u16 v20, v18 offset:43396
	ds_read_u16 v21, v18 offset:43916
	ds_read_u16 v22, v18 offset:44436
	s_waitcnt lgkmcnt(6)
	v_lshlrev_b32_e32 v11, 16, v7
	v_lshlrev_b32_e32 v10, 16, v6
	ds_read_b128 v[6:9], v168
	v_mov_b32_e32 v12, v2
	v_mov_b32_e32 v13, v4
	v_pk_add_f32 v[10:11], v[10:11], v[12:13] neg_lo:[0,1] neg_hi:[0,1]
	v_mov_b32_e32 v4, v3
	v_pk_mul_f32 v[2:3], v[4:5], v[10:11]
	s_waitcnt lgkmcnt(0)
	v_mov_b32_e32 v5, v8
	v_pk_fma_f32 v[10:11], v[98:99], v[2:3], v[100:101]
	v_add_u32_e32 v2, v165, v167
	v_lshlrev_b32_e32 v3, 16, v14
	ds_read_u16 v4, v2 offset:34816
	ds_read_u16 v14, v2 offset:35336
	ds_read_u16 v23, v2 offset:35856
	ds_read_u16 v24, v2 offset:42616
	ds_read_u16 v25, v2 offset:43136
	ds_read_u16 v113, v18 offset:61596
	s_waitcnt lgkmcnt(5)
	v_lshlrev_b32_e32 v2, 16, v4
	v_mov_b32_e32 v4, v6
	v_pk_add_f32 v[2:3], v[2:3], v[4:5] neg_lo:[0,1] neg_hi:[0,1]
	v_mov_b32_e32 v8, v7
	v_pk_mul_f32 v[6:7], v[8:9], v[2:3]
	ds_read_b128 v[2:5], v163
	v_pk_fma_f32 v[12:13], v[98:99], v[6:7], v[100:101]
	ds_read_b128 v[6:9], v166
	v_lshlrev_b32_e32 v15, 16, v15
	s_waitcnt lgkmcnt(6)
	v_lshlrev_b32_e32 v14, 16, v14
	s_waitcnt lgkmcnt(1)
	v_mov_b32_e32 v16, v2
	v_mov_b32_e32 v17, v4
	v_pk_add_f32 v[14:15], v[14:15], v[16:17] neg_lo:[0,1] neg_hi:[0,1]
	v_mov_b32_e32 v4, v3
	v_pk_mul_f32 v[2:3], v[4:5], v[14:15]
	s_waitcnt lgkmcnt(0)
	v_mov_b32_e32 v14, v6
	v_pk_fma_f32 v[4:5], v[98:99], v[2:3], v[100:101]
	v_lshlrev_b32_e32 v3, 16, v19
	v_lshlrev_b32_e32 v2, 16, v23
	v_mov_b32_e32 v15, v8
	v_pk_add_f32 v[2:3], v[2:3], v[14:15] neg_lo:[0,1] neg_hi:[0,1]
	v_mov_b32_e32 v8, v7
	v_pk_mul_f32 v[2:3], v[8:9], v[2:3]
	ds_read_b128 v[6:9], v185
	v_pk_fma_f32 v[14:15], v[98:99], v[2:3], v[100:101]
	v_cvt_pk_bf16_f32 v2, v10, v11
	v_cvt_pk_bf16_f32 v3, v12, v13
	ds_read_b128 v[10:13], v186
	v_cvt_pk_bf16_f32 v4, v4, v5
	v_cvt_pk_bf16_f32 v5, v14, v15
	v_lshlrev_b32_e32 v15, 16, v20
	v_lshlrev_b32_e32 v14, 16, v24
	s_waitcnt lgkmcnt(1)
	v_mov_b32_e32 v16, v6
	v_mov_b32_e32 v17, v8
	v_pk_add_f32 v[14:15], v[14:15], v[16:17] neg_lo:[0,1] neg_hi:[0,1]
	v_mov_b32_e32 v8, v7
	v_pk_mul_f32 v[6:7], v[8:9], v[14:15]
	s_waitcnt lgkmcnt(0)
	v_mov_b32_e32 v8, v10
	v_pk_fma_f32 v[14:15], v[98:99], v[6:7], v[100:101]
	v_lshlrev_b32_e32 v7, 16, v21
	v_lshlrev_b32_e32 v6, 16, v25
	v_mov_b32_e32 v9, v12
	v_pk_add_f32 v[16:17], v[6:7], v[8:9] neg_lo:[0,1] neg_hi:[0,1]
	ds_read_u16 v19, v187 offset:34816
	ds_read_u16 v20, v187 offset:35336
	ds_read_u16 v21, v187 offset:42096
	ds_read_b128 v[6:9], v188
	v_mov_b32_e32 v12, v11
	v_pk_mul_f32 v[10:11], v[12:13], v[16:17]
	v_lshlrev_b32_e32 v13, 16, v22
	s_waitcnt lgkmcnt(3)
	v_lshlrev_b32_e32 v12, 16, v19
	s_waitcnt lgkmcnt(0)
	v_mov_b32_e32 v16, v6
	v_mov_b32_e32 v17, v8
	v_pk_add_f32 v[12:13], v[12:13], v[16:17] neg_lo:[0,1] neg_hi:[0,1]
	v_mov_b32_e32 v8, v7
	v_pk_mul_f32 v[6:7], v[8:9], v[12:13]
	v_pk_fma_f32 v[10:11], v[98:99], v[10:11], v[100:101]
	v_pk_fma_f32 v[12:13], v[98:99], v[6:7], v[100:101]
	ds_read_b128 v[6:9], v189
	ds_read_u16 v16, v18 offset:44956
	ds_read_u16 v22, v18 offset:51716
	ds_read_u16 v23, v18 offset:52236
	ds_read_u16 v24, v18 offset:52756
	ds_read_u16 v26, v18 offset:53276
	ds_read_u16 v27, v18 offset:60036
	ds_read_u16 v28, v18 offset:60556
	ds_read_u16 v36, v18 offset:61076
	s_waitcnt lgkmcnt(7)
	v_lshlrev_b32_e32 v17, 16, v16
	v_lshlrev_b32_e32 v16, 16, v20
	v_mov_b32_e32 v18, v6
	v_mov_b32_e32 v19, v8
	v_pk_add_f32 v[16:17], v[16:17], v[18:19] neg_lo:[0,1] neg_hi:[0,1]
	v_mov_b32_e32 v8, v7
	v_pk_mul_f32 v[6:7], v[8:9], v[16:17]
	ds_read_u16 v25, v187 offset:42616
	ds_read_u16 v29, v187 offset:43136
	v_pk_fma_f32 v[16:17], v[98:99], v[6:7], v[100:101]
	v_cvt_pk_bf16_f32 v7, v10, v11
	v_cvt_pk_bf16_f32 v8, v12, v13
	ds_read_b128 v[10:13], v190
	v_cvt_pk_bf16_f32 v6, v14, v15
	v_cvt_pk_bf16_f32 v9, v16, v17
	ds_read_b128 v[14:17], v191
	s_waitcnt lgkmcnt(10)
	v_lshlrev_b32_e32 v19, 16, v22
	v_lshlrev_b32_e32 v18, 16, v21
	s_waitcnt lgkmcnt(1)
	v_mov_b32_e32 v20, v10
	v_mov_b32_e32 v21, v12
	v_pk_add_f32 v[18:19], v[18:19], v[20:21] neg_lo:[0,1] neg_hi:[0,1]
	v_mov_b32_e32 v12, v11
	v_pk_mul_f32 v[10:11], v[12:13], v[18:19]
	s_waitcnt lgkmcnt(0)
	v_mov_b32_e32 v12, v14
	v_pk_fma_f32 v[18:19], v[98:99], v[10:11], v[100:101]
	v_lshlrev_b32_e32 v11, 16, v23
	v_lshlrev_b32_e32 v10, 16, v25
	v_mov_b32_e32 v13, v16
	v_pk_add_f32 v[10:11], v[10:11], v[12:13] neg_lo:[0,1] neg_hi:[0,1]
	v_mov_b32_e32 v16, v15
	v_pk_mul_f32 v[14:15], v[16:17], v[10:11]
	ds_read_b128 v[10:13], v192
	v_pk_fma_f32 v[20:21], v[98:99], v[14:15], v[100:101]
	ds_read_b128 v[14:17], v194
	v_lshlrev_b32_e32 v23, 16, v24
	v_lshlrev_b32_e32 v22, 16, v29
	s_waitcnt lgkmcnt(1)
	v_mov_b32_e32 v24, v10
	v_mov_b32_e32 v25, v12
	v_pk_add_f32 v[22:23], v[22:23], v[24:25] neg_lo:[0,1] neg_hi:[0,1]
	v_mov_b32_e32 v12, v11
	v_pk_mul_f32 v[10:11], v[12:13], v[22:23]
	s_waitcnt lgkmcnt(0)
	v_mov_b32_e32 v22, v14
	v_pk_fma_f32 v[12:13], v[98:99], v[10:11], v[100:101]
	ds_read_u16 v10, v193 offset:34816
	ds_read_u16 v24, v193 offset:41576
	ds_read_u16 v29, v193 offset:42096
	ds_read_u16 v38, v193 offset:42616
	ds_read_u16 v121, v193 offset:43136
	v_lshlrev_b32_e32 v11, 16, v26
	s_waitcnt lgkmcnt(4)
; #define LAS __attribute__((address_space(3)))
; #define MFMA16(A, B, Cc) __builtin_amdgcn_mfma_f32_16x16x32_bf16((A), (B), (Cc), 0, 0, 0)
; #define PIN(x) asm volatile("" : "+v"(x))
; __device__ __forceinline__ float bf_lo(unsigned w) { return __uint_as_float(w << 16); }
; __device__ __forceinline__ unsigned pk4f8(float a, float b, float c, float d) { int p = __builtin_amdgcn_cvt_pk_fp8_f32(sat8(a), sat8(b), 0, false); p = __builtin_amdgcn_cvt_pk_fp8_f32(sat8(c), sat8(d), p, true); return (unsigned)p; }
; __device__ __forceinline__ float bf_hi(unsigned w) { return __uint_as_float(w & 0xffff0000u); }
; __device__ __forceinline__ void gmlp_compute(GmlpRegs& R, const Args& a, const Ctx& C, int c, int hd) {
;     ...
;     f32x4 acc[8];
; #pragma unroll
;     for (int nt = 0; nt < 8; ++nt) { acc[nt] = (f32x4){0.f, 0.f, 0.f, 0.f};
; #pragma unroll
;         for (int ks = 0; ks <= nt / 2; ++ks) acc[nt] = MFMA16(af[ks], *(const LAS bf16x8*)(WL + (16 * nt + fr) * 272 + (32 * ks + 8 * q) * 2), acc[nt]); }
; #pragma unroll
;     for (int nt = 0; nt < 8; ++nt) PIN(R.uq[nt]);
; #pragma unroll
;     for (int nt = 0; nt < 8; ++nt) { const size_t row = T0 + 16 * nt + fr; const float bs = R.bsv[nt];
;         const float o0 = bf_lo(R.uq[nt].x) * (acc[nt][0] + bs), o1 = bf_hi(R.uq[nt].x) * (acc[nt][1] + bs);
;         const float o2 = bf_lo(R.uq[nt].y) * (acc[nt][2] + bs), o3 = bf_hi(R.uq[nt].y) * (acc[nt][3] + bs);
;         *(unsigned*)((unsigned char*)Y + row * DM + chs) = pk4f8(o0, o1, o2, o3); }
	v_lshlrev_b32_e32 v10, 16, v10
	v_mov_b32_e32 v23, v16
	v_pk_add_f32 v[10:11], v[10:11], v[22:23] neg_lo:[0,1] neg_hi:[0,1]
	v_mov_b32_e32 v16, v15
	v_pk_mul_f32 v[10:11], v[16:17], v[10:11]
	ds_read_b128 v[14:17], v195
	v_pk_fma_f32 v[22:23], v[98:99], v[10:11], v[100:101]
	v_cvt_pk_bf16_f32 v10, v18, v19
	v_cvt_pk_bf16_f32 v11, v20, v21
	v_cvt_pk_bf16_f32 v12, v12, v13
	v_cvt_pk_bf16_f32 v13, v22, v23
	v_lshlrev_b32_e32 v23, 16, v27
	s_waitcnt lgkmcnt(4)
	v_lshlrev_b32_e32 v22, 16, v24
	ds_read_b128 v[18:21], v196
	s_waitcnt lgkmcnt(1)
	v_mov_b32_e32 v24, v14
	v_mov_b32_e32 v25, v16
	v_pk_add_f32 v[26:27], v[22:23], v[24:25] neg_lo:[0,1] neg_hi:[0,1]
	v_mov_b32_e32 v16, v15
	v_add_u32_e32 v126, v199, v200
	v_pk_mul_f32 v[14:15], v[16:17], v[26:27]
	v_lshlrev_b32_e32 v31, 16, v28
	v_lshlrev_b32_e32 v30, 16, v29
	ds_read_b128 v[26:29], v126 offset:8704
	s_waitcnt lgkmcnt(1)
	v_mov_b32_e32 v32, v18
	v_mov_b32_e32 v33, v20
	v_pk_add_f32 v[34:35], v[30:31], v[32:33] neg_lo:[0,1] neg_hi:[0,1]
	ds_read_b128 v[30:33], v126 offset:8768
	v_mov_b32_e32 v20, v19
	s_waitcnt lgkmcnt(1)
	v_mfma_f32_16x16x32_bf16 v[26:29], v[2:5], v[26:29], 0
	v_mul_f32_e64 v34, v20, v34
	v_mul_f32_e64 v35, v21, v35
	ds_read_b128 v[18:21], v126 offset:13056
	v_lshlrev_b32_e32 v46, 16, v38
	ds_read_b128 v[38:41], v126 offset:17408
	ds_read_b128 v[42:45], v126 offset:17472
	s_waitcnt lgkmcnt(3)
	v_mfma_f32_16x16x32_bf16 v[26:29], v[6:9], v[30:33], v[26:29]
	v_fma_f32 v92, v98, v34, v100
	v_fma_f32 v93, v99, v35, v101
	v_lshlrev_b32_e32 v47, 16, v36
	ds_read_b128 v[30:33], v126 offset:13120
	ds_read_b128 v[34:37], v197
	s_waitcnt lgkmcnt(4)
	v_mfma_f32_16x16x32_bf16 v[18:21], v[2:5], v[18:21], 0
	v_fma_f32 v88, v98, v14, v100
	v_fma_f32 v89, v99, v15, v101
	ds_read_b128 v[22:25], v126
	ds_read_b128 v[14:17], v126 offset:4352
	s_waitcnt lgkmcnt(5)
	v_mfma_f32_16x16x32_bf16 v[38:41], v[2:5], v[38:41], 0
	s_lshl_b64 s[4:5], s[70:71], 11
	s_mov_b64 s[8:9], 0x2300000
	v_readlane_b32 s16, v249, 1
	s_waitcnt lgkmcnt(3)
	v_mfma_f32_16x16x32_bf16 v[18:21], v[6:9], v[30:33], v[18:21]
	ds_read_b128 v[30:33], v198
	s_waitcnt lgkmcnt(3)
	v_mov_b32_e32 v48, v34
	v_mov_b32_e32 v49, v36
	v_pk_add_f32 v[90:91], v[46:47], v[48:49] neg_lo:[0,1] neg_hi:[0,1]
	v_mov_b32_e32 v36, v35
	ds_read_b128 v[46:49], v126 offset:17536
	v_mfma_f32_16x16x32_bf16 v[38:41], v[6:9], v[42:45], v[38:41]
	v_mul_f32_e64 v42, v36, v90
	v_mul_f32_e64 v43, v37, v91
	ds_read_b128 v[34:37], v126 offset:21760
	v_pk_fma_f32 v[122:123], v[98:99], v[42:43], v[100:101]
	ds_read_b128 v[42:45], v126 offset:21824
	s_waitcnt lgkmcnt(1)
	v_mfma_f32_16x16x32_bf16 v[34:37], v[2:5], v[34:37], 0
	v_lshlrev_b32_e32 v91, 16, v113
	v_lshlrev_b32_e32 v90, 16, v121
	v_mov_b32_e32 v124, v30
	v_mfma_f32_16x16x32_bf16 v[38:41], v[10:13], v[46:49], v[38:41]
	ds_read_b128 v[46:49], v126 offset:21888
	v_mov_b32_e32 v125, v32
	v_pk_add_f32 v[90:91], v[90:91], v[124:125] neg_lo:[0,1] neg_hi:[0,1]
	s_waitcnt lgkmcnt(1)
	v_mfma_f32_16x16x32_bf16 v[34:37], v[6:9], v[42:45], v[34:37]
	ds_read_b128 v[42:45], v126 offset:26112
	v_mov_b32_e32 v32, v31
	v_readlane_b32 s17, v249, 2
	s_waitcnt lgkmcnt(1)
	v_mfma_f32_16x16x32_bf16 v[34:37], v[10:13], v[46:49], v[34:37]
	v_mul_f32_e64 v46, v32, v90
	v_mul_f32_e64 v47, v33, v91
	ds_read_b128 v[30:33], v126 offset:26176
	v_pk_fma_f32 v[98:99], v[98:99], v[46:47], v[100:101]
	s_waitcnt lgkmcnt(1)
	v_mfma_f32_16x16x32_bf16 v[42:45], v[2:5], v[42:45], 0
	v_cvt_pk_bf16_f32 v46, v88, v89
	ds_read_b128 v[88:91], v126 offset:26240
	v_cvt_pk_bf16_f32 v47, v92, v93
	s_waitcnt lgkmcnt(1)
	v_mfma_f32_16x16x32_bf16 v[30:33], v[6:9], v[30:33], v[42:45]
	v_cvt_pk_bf16_f32 v48, v122, v123
	v_cvt_pk_bf16_f32 v49, v98, v99
	v_readlane_b32 s18, v249, 3
	ds_read_b128 v[42:45], v126 offset:26304
	s_waitcnt lgkmcnt(1)
	v_mfma_f32_16x16x32_bf16 v[30:33], v[10:13], v[88:91], v[30:33]
	v_readlane_b32 s19, v249, 4
	v_readlane_b32 s20, v249, 5
	v_readlane_b32 s21, v249, 6
	s_waitcnt lgkmcnt(0)
	v_mfma_f32_16x16x32_bf16 v[30:33], v[46:49], v[42:45], v[30:33]
	ds_read_b128 v[42:45], v126 offset:30464
	ds_read_b128 v[88:91], v126 offset:30528
	v_readlane_b32 s22, v249, 7
	v_readlane_b32 s23, v249, 8
	v_mfma_f32_16x16x32_bf16 v[22:25], v[2:5], v[22:25], 0
	v_readlane_b32 s24, v249, 9
	v_readlane_b32 s25, v249, 10
	v_readlane_b32 s26, v249, 11
	v_mfma_f32_16x16x32_bf16 v[14:17], v[2:5], v[14:17], 0
	v_readlane_b32 s27, v249, 12
	v_readlane_b32 s28, v249, 13
	v_readlane_b32 s29, v249, 14
	s_waitcnt lgkmcnt(1)
	v_mfma_f32_16x16x32_bf16 v[2:5], v[2:5], v[42:45], 0
	v_readlane_b32 s30, v249, 15
	v_readlane_b32 s31, v249, 16
	s_mov_b64 s[14:15], s[22:23]
	s_waitcnt lgkmcnt(0)
	v_mfma_f32_16x16x32_bf16 v[2:5], v[6:9], v[88:91], v[2:5]
	ds_read_b128 v[6:9], v126 offset:30592
	ds_read_b128 v[42:45], v126 offset:30656
	s_waitcnt vmcnt(17)
	s_waitcnt vmcnt(16)
	s_waitcnt lgkmcnt(1)
	v_mfma_f32_16x16x32_bf16 v[2:5], v[10:13], v[6:9], v[2:5]
	v_lshlrev_b32_e32 v6, 16, v110
	v_add_f32_e32 v7, v161, v22
	v_mul_f32_e32 v6, v7, v6
	v_and_b32_e32 v7, 0xffff0000, v110
	v_add_f32_e32 v8, v161, v23
	v_mul_f32_e32 v7, v8, v7
	v_med3_f32 v6, v6, s1, v128
	v_med3_f32 v7, v7, s1, v128
	v_mov_b32_e32 v11, 0
	v_lshlrev_b32_e32 v8, 16, v111
	v_add_f32_e32 v9, v161, v24
	v_cvt_pk_fp8_f32 v11, v6, v7
	v_mul_f32_e32 v8, v9, v8
	v_and_b32_e32 v9, 0xffff0000, v111
	v_add_f32_e32 v10, v161, v25
	v_mul_f32_e32 v6, v10, v9
	v_med3_f32 v7, v8, s1, v128
	v_med3_f32 v6, v6, s1, v128
	v_cvt_pk_fp8_f32 v11, v7, v6 op_sel:[0,0,1]
	v_lshlrev_b32_e32 v8, 16, v118
	v_add_f32_e32 v9, v160, v14
	v_mul_f32_e32 v8, v9, v8
	v_and_b32_e32 v9, 0xffff0000, v118
	v_add_f32_e32 v10, v160, v15
	v_lshlrev_b64 v[6:7], 11, v[116:117]
	v_and_b32_e32 v231, 0x7f, v116
	v_and_b32_e32 v232, 0xffffff80, v116
	s_movk_i32 s88, 0x90
	v_mad_u32_u24 v233, v231, s88, v230
	v_add_u32_e32 v233, 0x12000, v233
	v_mul_f32_e32 v9, v10, v9
	v_lshl_add_u64 v[6:7], v[142:143], 0, v[6:7]
	v_med3_f32 v8, v8, s1, v128
	v_med3_f32 v9, v9, s1, v128
	v_mov_b32_e32 v13, 0
	s_waitcnt vmcnt(15)
; __device__ __forceinline__ float bf_lo(unsigned w) { return __uint_as_float(w << 16); }
; __device__ __forceinline__ unsigned pk4f8(float a, float b, float c, float d) { int p = __builtin_amdgcn_cvt_pk_fp8_f32(sat8(a), sat8(b), 0, false); p = __builtin_amdgcn_cvt_pk_fp8_f32(sat8(c), sat8(d), p, true); return (unsigned)p; }
; __device__ __forceinline__ float bf_hi(unsigned w) { return __uint_as_float(w & 0xffff0000u); }
; __device__ __forceinline__ void gmlp_compute(GmlpRegs& R, const Args& a, const Ctx& C, int c, int hd) {
;     ...
;     for (int nt = 0; nt < 8; ++nt) { const size_t row = T0 + 16 * nt + fr; const float bs = R.bsv[nt];
;         const float o0 = bf_lo(R.uq[nt].x) * (acc[nt][0] + bs), o1 = bf_hi(R.uq[nt].x) * (acc[nt][1] + bs);
;         const float o2 = bf_lo(R.uq[nt].y) * (acc[nt][2] + bs), o3 = bf_hi(R.uq[nt].y) * (acc[nt][3] + bs);
;         *(unsigned*)((unsigned char*)Y + row * DM + chs) = pk4f8(o0, o1, o2, o3); }
	s_waitcnt vmcnt(14)
	s_waitcnt vmcnt(13)
	s_waitcnt vmcnt(12)
	s_waitcnt vmcnt(11)
	s_waitcnt vmcnt(10)
	ds_write_b32 v233, v11
	v_lshlrev_b32_e32 v10, 16, v119
	v_add_f32_e32 v11, v160, v16
	v_cvt_pk_fp8_f32 v13, v8, v9
	v_mul_f32_e32 v10, v11, v10
	v_and_b32_e32 v11, 0xffff0000, v119
	v_add_f32_e32 v12, v160, v17
	v_mul_f32_e32 v8, v12, v11
	v_med3_f32 v9, v10, s1, v128
	v_med3_f32 v8, v8, s1, v128
	v_cvt_pk_fp8_f32 v13, v9, v8 op_sel:[0,0,1]
	v_add_co_u32_e32 v8, vcc, s2, v6
	v_add_f32_e32 v10, v159, v27
	s_nop 0
	v_addc_co_u32_e32 v9, vcc, 0, v7, vcc
	ds_write_b32 v233, v13 offset:2304
	v_lshlrev_b32_e32 v8, 16, v114
	v_add_f32_e32 v9, v159, v26
	v_mul_f32_e32 v8, v9, v8
	v_and_b32_e32 v9, 0xffff0000, v114
	v_mul_f32_e32 v9, v10, v9
	v_med3_f32 v8, v8, s1, v128
	v_med3_f32 v9, v9, s1, v128
	v_mov_b32_e32 v13, 0
	v_lshlrev_b32_e32 v10, 16, v115
	v_add_f32_e32 v11, v159, v28
	v_cvt_pk_fp8_f32 v13, v8, v9
	v_mul_f32_e32 v10, v11, v10
	v_and_b32_e32 v11, 0xffff0000, v115
	v_add_f32_e32 v12, v159, v29
	v_mul_f32_e32 v8, v12, v11
	v_med3_f32 v9, v10, s1, v128
	v_med3_f32 v8, v8, s1, v128
	v_cvt_pk_fp8_f32 v13, v9, v8 op_sel:[0,0,1]
	v_add_co_u32_e32 v8, vcc, s33, v6
	v_add_f32_e32 v10, v156, v19
	s_nop 0
	v_addc_co_u32_e32 v9, vcc, 0, v7, vcc
	ds_write_b32 v233, v13 offset:4608
	v_lshlrev_b32_e32 v8, 16, v108
	v_add_f32_e32 v9, v156, v18
	v_mul_f32_e32 v8, v9, v8
	v_and_b32_e32 v9, 0xffff0000, v108
	v_mul_f32_e32 v9, v10, v9
	v_med3_f32 v8, v8, s1, v128
	v_med3_f32 v9, v9, s1, v128
	v_mov_b32_e32 v13, 0
	v_lshlrev_b32_e32 v10, 16, v109
	v_add_f32_e32 v11, v156, v20
	v_cvt_pk_fp8_f32 v13, v8, v9
	v_mul_f32_e32 v10, v11, v10
	v_and_b32_e32 v11, 0xffff0000, v109
	v_add_f32_e32 v12, v156, v21
	v_mul_f32_e32 v8, v12, v11
	v_med3_f32 v9, v10, s1, v128
	v_med3_f32 v8, v8, s1, v128
	v_cvt_pk_fp8_f32 v13, v9, v8 op_sel:[0,0,1]
	v_add_co_u32_e32 v8, vcc, s74, v6
	v_add_f32_e32 v10, v154, v39
	s_nop 0
	v_addc_co_u32_e32 v9, vcc, 0, v7, vcc
	ds_write_b32 v233, v13 offset:6912
	v_lshlrev_b32_e32 v8, 16, v106
	v_add_f32_e32 v9, v154, v38
	v_mul_f32_e32 v8, v9, v8
	v_and_b32_e32 v9, 0xffff0000, v106
	v_mul_f32_e32 v9, v10, v9
	v_med3_f32 v8, v8, s1, v128
	v_med3_f32 v9, v9, s1, v128
	v_mov_b32_e32 v13, 0
	v_lshlrev_b32_e32 v10, 16, v107
	v_add_f32_e32 v11, v154, v40
	v_cvt_pk_fp8_f32 v13, v8, v9
	v_mul_f32_e32 v10, v11, v10
	v_and_b32_e32 v11, 0xffff0000, v107
	v_add_f32_e32 v12, v154, v41
	v_mul_f32_e32 v8, v12, v11
	v_med3_f32 v9, v10, s1, v128
	v_med3_f32 v8, v8, s1, v128
	v_cvt_pk_fp8_f32 v13, v9, v8 op_sel:[0,0,1]
	v_add_co_u32_e32 v8, vcc, s75, v6
	v_add_f32_e32 v10, v152, v35
	s_nop 0
	v_addc_co_u32_e32 v9, vcc, 0, v7, vcc
	ds_write_b32 v233, v13 offset:9216
	v_lshlrev_b32_e32 v8, 16, v104
	v_add_f32_e32 v9, v152, v34
	v_mul_f32_e32 v8, v9, v8
	v_and_b32_e32 v9, 0xffff0000, v104
	v_mul_f32_e32 v9, v10, v9
	v_med3_f32 v8, v8, s1, v128
	v_med3_f32 v9, v9, s1, v128
	v_mov_b32_e32 v13, 0
	v_lshlrev_b32_e32 v10, 16, v105
	v_add_f32_e32 v11, v152, v36
	v_cvt_pk_fp8_f32 v13, v8, v9
	v_mul_f32_e32 v10, v11, v10
	v_and_b32_e32 v11, 0xffff0000, v105
	v_add_f32_e32 v12, v152, v37
	v_mul_f32_e32 v8, v12, v11
	v_med3_f32 v9, v10, s1, v128
	v_med3_f32 v8, v8, s1, v128
	v_cvt_pk_fp8_f32 v13, v9, v8 op_sel:[0,0,1]
	v_add_co_u32_e32 v8, vcc, s76, v6
	v_add_f32_e32 v10, v151, v31
	s_nop 0
	v_addc_co_u32_e32 v9, vcc, 0, v7, vcc
	ds_write_b32 v233, v13 offset:11520
	v_lshlrev_b32_e32 v8, 16, v102
	v_add_f32_e32 v9, v151, v30
	v_mul_f32_e32 v8, v9, v8
	v_and_b32_e32 v9, 0xffff0000, v102
	v_mul_f32_e32 v9, v10, v9
	v_med3_f32 v8, v8, s1, v128
	v_med3_f32 v9, v9, s1, v128
	v_mov_b32_e32 v13, 0
	v_lshlrev_b32_e32 v10, 16, v103
	v_add_f32_e32 v11, v151, v32
	v_cvt_pk_fp8_f32 v13, v8, v9
	v_mul_f32_e32 v10, v11, v10
	v_and_b32_e32 v11, 0xffff0000, v103
	v_add_f32_e32 v12, v151, v33
	v_mul_f32_e32 v8, v12, v11
	v_med3_f32 v9, v10, s1, v128
	v_med3_f32 v8, v8, s1, v128
	s_waitcnt lgkmcnt(0)
	v_mfma_f32_16x16x32_bf16 v[2:5], v[46:49], v[42:45], v[2:5]
	v_cvt_pk_fp8_f32 v13, v9, v8 op_sel:[0,0,1]
	v_add_co_u32_e32 v8, vcc, s77, v6
	v_mov_b32_e32 v111, 0
	s_nop 0
	v_addc_co_u32_e32 v9, vcc, 0, v7, vcc
	ds_write_b32 v233, v13 offset:13824
	v_lshlrev_b32_e32 v8, 16, v96
	s_nop 0
	v_add_f32_e32 v2, v150, v2
	v_mul_f32_e32 v2, v2, v8
	v_and_b32_e32 v8, 0xffff0000, v96
	v_add_f32_e32 v3, v150, v3
	v_mul_f32_e32 v3, v3, v8
	v_lshlrev_b32_e32 v8, 16, v97
	v_add_f32_e32 v4, v150, v4
	v_mul_f32_e32 v4, v4, v8
	v_and_b32_e32 v8, 0xffff0000, v97
	v_add_f32_e32 v5, v150, v5
	v_med3_f32 v2, v2, s1, v128
	v_med3_f32 v3, v3, s1, v128
	v_mov_b32_e32 v9, 0
	v_cvt_pk_fp8_f32 v9, v2, v3
	v_mul_f32_e32 v2, v5, v8
	v_med3_f32 v3, v4, s1, v128
	v_med3_f32 v2, v2, s1, v128
	s_mul_i32 s1, s0, 0x2100
	s_add_u32 s4, s1, s4
	s_addc_u32 s5, 0, s5
	s_lshl_b64 s[4:5], s[4:5], 5
	s_lshl_b32 s1, s0, 9
	s_lshl_b32 s2, s0, 12
	s_add_u32 s6, s94, s1
	v_cvt_pk_fp8_f32 v9, v3, v2 op_sel:[0,0,1]
	v_add_co_u32_e32 v2, vcc, s78, v6
	v_lshlrev_b32_e32 v110, 2, v153
	s_addc_u32 s7, s95, 0
	v_addc_co_u32_e32 v3, vcc, 0, v7, vcc
	v_lshl_add_u64 v[18:19], s[6:7], 0, v[110:111]
	s_mov_b32 s1, 0x2300000
	v_lshl_add_u64 v[20:21], v[18:19], 0, s[8:9]
	v_add_co_u32_e32 v18, vcc, s1, v18
	ds_write_b32 v233, v9 offset:16128
	s_waitcnt lgkmcnt(0)
	s_barrier
; __device__ __forceinline__ void s5_load_consts(S5C& K, const Args& a, int g, int lane) {
;     const int fr = lane & 15, q = lane >> 4;
;     const float* ABAR = (const float*)(a.ws + WS_S5C + S5C_ABAR) + (size_t)g * 128;
;     const bf16* BBAR = (const bf16*)(a.ws + WS_S5C + S5C_BBAR) + (size_t)g * 2048;
; #pragma unroll
; __device__ __forceinline__ void s5_prompt_task(const Args& a, const Ctx& C, int b, int g, v4u (&xv)[8]) {
;     const bf16* PROJ = (const bf16*)(a.ws + WS_PROJ); bf16* Y = (bf16*)(a.ws + WS_Y);
;     LAS unsigned char* XS = C.lds;
;     LAS float* SH = (LAS float*)(C.lds + 67584);
;     LAS float* TW = (LAS float*)(C.lds + 67584 + 128 * 132 * 4);
;     const int lane = C.lane, n = lane & 15, q = lane >> 4, w = C.wave;
;     const size_t row0 = (size_t)b * SEQ;
;     const bf16* XBg = (const bf16*)(a.ws + WS_XB) + ((size_t)g * MP + row0) * 16; const bf16* ZBg = (const bf16*)(a.ws + WS_ZB) + ((size_t)g * MP + row0) * 16;
;     __syncthreads();
; #pragma unroll
;     for (int i = 0; i < 8; ++i) PIN(xv[i]);
; #pragma unroll
;     for (int i = 0; i < 8; ++i) { const int idx = C.tid + 512 * i, tok = idx >> 1; *(LAS v4u*)(XS + tok * 32 + (tok >> 4) * 16 + (idx & 1) * 16) = xv[i]; }
;     S5C K; s5_load_consts(K, a, g, lane);
;     __syncthreads();
;     const int chunk = 16 * w + n;
;     f32x4 hre[4], him[4];
; #pragma unroll
;     for (int j = 0; j < 4; ++j) { hre[j] = (f32x4){0.f, 0.f, 0.f, 0.f}; him[j] = (f32x4){0.f, 0.f, 0.f, 0.f}; }
;     const LAS unsigned char* xsl = XS + chunk * 528 + q * 8;
;     for (int t = 0; t < 16; ++t) { const v2u xq = *(const LAS v2u*)(xsl + t * 32); S5_UPDATE(K, hre, him, xq); }
; #pragma unroll
;     for (int j = 0; j < 4; ++j) { LAS float* d = SH + chunk * 132 + 2 * (16 * j + 4 * q);
;         *(LAS f32x4*)d = (f32x4){hre[j][0], him[j][0], hre[j][1], him[j][1]}; *(LAS f32x4*)(d + 4) = (f32x4){hre[j][2], him[j][2], hre[j][3], him[j][3]}; }
;     v2u zq[4];
; #pragma unroll
;     for (int t = 0; t < 4; ++t) zq[t] = __builtin_nontemporal_load((const v2u*)(ZBg + (size_t)(16 * chunk + t) * 16 + 4 * q));
;     LDS_WAIT();
;     { const float* A16 = (const float*)(a.ws + WS_S5C + S5C_A16) + (size_t)g * 128; const float* A256 = (const float*)(a.ws + WS_S5C + S5C_A256) + (size_t)g * 128;
;       const float a16r = A16[2 * lane], a16i = A16[2 * lane + 1], a256r = A256[2 * lane], a256i = A256[2 * lane + 1];
	v_lshrrev_b32_e32 v234, 3, v0
	v_and_b32_e32 v236, 7, v0
	v_lshlrev_b32_e32 v236, 4, v236
	s_movk_i32 s88, 0x90
	v_mad_u32_u24 v221, v234, s88, v236
	v_add_u32_e32 v221, 0x12000, v221
	ds_read_b128 v[238:241], v221
	ds_read_b128 v[242:245], v221 offset:9216
	v_add_u32_e32 v234, v232, v234
	v_mov_b32_e32 v235, 0
	v_mov_b32_e32 v237, 0
	v_lshlrev_b64 v[246:247], 11, v[234:235]
	v_lshl_add_u64 v[246:247], v[228:229], 0, v[246:247]
	v_lshl_add_u64 v[246:247], v[246:247], 0, v[236:237]
	v_mov_b32_e32 v236, 0x20000
	v_lshl_add_u64 v[212:213], v[246:247], 0, v[236:237]
	s_waitcnt lgkmcnt(0)
	global_store_dwordx4 v[246:247], v[238:241], off
	global_store_dwordx4 v[212:213], v[242:245], off
	s_nop 0
	v_addc_co_u32_e32 v19, vcc, 0, v19, vcc
	s_barrier
	s_waitcnt vmcnt(9)
	s_waitcnt vmcnt(8)
	s_waitcnt vmcnt(7)
	s_waitcnt vmcnt(6)
	s_waitcnt vmcnt(5)
	s_waitcnt vmcnt(4)
	s_waitcnt vmcnt(3)
	s_waitcnt vmcnt(2)
	global_load_dwordx4 v[2:5], v[20:21], off offset:16
	global_load_dwordx4 v[6:9], v[20:21], off offset:144
	global_load_dwordx4 v[10:13], v[20:21], off offset:272
	global_load_dwordx4 v[14:17], v[20:21], off offset:400
	global_load_dwordx4 v[30:33], v[18:19], off
	v_and_b32_e32 v18, 0x1fe0, v94
	v_lshrrev_b32_e32 v19, 1, v0
	v_add_u32_e32 v18, 0, v18
	v_and_b32_e32 v19, 0xf0, v19
	v_and_b32_e32 v24, 16, v94
	v_add3_u32 v18, v18, v19, v24
	ds_write_b128 v18, v[74:77]
	v_and_b32_e32 v18, 0x3fe0, v87
	v_lshrrev_b32_e32 v19, 1, v146
	v_add_u32_e32 v18, 0, v18
	v_and_b32_e32 v19, 0x1f0, v19
	v_add3_u32 v18, v18, v19, v24
	ds_write_b128 v18, v[78:81]
	v_and_b32_e32 v18, 0x7fe0, v148
	v_lshrrev_b32_e32 v19, 1, v147
	v_add_u32_e32 v18, 0, v18
	v_and_b32_e32 v19, 0x3f0, v19
	v_add3_u32 v18, v18, v19, v24
	ds_write_b128 v18, v[70:73]
	v_and_b32_e32 v18, 0x7fe0, v86
	v_lshrrev_b32_e32 v19, 1, v95
	v_add_u32_e32 v18, 0, v18
	v_and_b32_e32 v19, 0x3f0, v19
	v_add3_u32 v18, v18, v19, v24
	ds_write_b128 v18, v[66:69]
	v_and_b32_e32 v18, 0xbfe0, v85
	v_lshrrev_b32_e32 v19, 1, v120
	v_add_u32_e32 v18, 0, v18
	v_and_b32_e32 v19, 0x5f0, v19
	v_add3_u32 v18, v18, v19, v24
	ds_write_b128 v18, v[58:61]
	v_and_b32_e32 v18, 0xffe0, v84
	v_lshrrev_b32_e32 v19, 1, v157
	v_add_u32_e32 v18, 0, v18
	v_and_b32_e32 v19, 0x7f0, v19
	v_add3_u32 v18, v18, v19, v24
	ds_write_b128 v18, v[62:65]
	v_and_b32_e32 v18, 0xffe0, v83
	v_lshrrev_b32_e32 v19, 1, v158
	s_add_u32 s8, s94, s2
	v_add_u32_e32 v18, 0, v18
	v_and_b32_e32 v19, 0x7f0, v19
	s_addc_u32 s9, s95, 0
	v_lshlrev_b32_e32 v110, 1, v112
	v_add3_u32 v25, v18, v19, v24
	v_lshl_add_u64 v[18:19], s[8:9], 0, v[110:111]
	v_lshlrev_b32_e32 v22, 5, v149
	v_mov_b32_e32 v23, v111
	v_lshl_add_u64 v[18:19], v[18:19], 0, v[22:23]
	s_mov_b32 s1, 0x2320000
	v_add_co_u32_e32 v22, vcc, s1, v18
	s_mov_b64 s[8:9], 0x2320000
	s_nop 0
	v_addc_co_u32_e32 v23, vcc, 0, v19, vcc
	global_load_dwordx2 v[114:115], v[22:23], off
	v_lshl_add_u64 v[18:19], v[18:19], 0, s[8:9]
	global_load_dwordx2 v[116:117], v[18:19], off offset:512
	global_load_dwordx4 v[70:73], v[20:21], off offset:128
	v_and_b32_e32 v22, 0xffe0, v82
	v_lshrrev_b32_e32 v23, 1, v155
	global_load_dwordx4 v[74:77], v[20:21], off offset:256
	global_load_dwordx4 v[66:69], v[20:21], off offset:384
	v_add_u32_e32 v22, 0, v22
	v_and_b32_e32 v23, 0x7f0, v23
	v_add3_u32 v22, v22, v23, v24
	ds_write_b128 v25, v[50:53]
	ds_write_b128 v22, v[54:57]
	global_load_dwordx2 v[126:127], v[18:19], off offset:1024
	global_load_dwordx2 v[128:129], v[18:19], off offset:1536
	global_load_dwordx2 v[130:131], v[18:19], off offset:2048
	global_load_dwordx2 v[132:133], v[18:19], off offset:2560
	global_load_dwordx2 v[134:135], v[18:19], off offset:3072
	global_load_dwordx2 v[136:137], v[18:19], off offset:3584
	v_lshl_or_b32 v18, v149, 8, s2
	v_mov_b32_e32 v19, v111
	s_mov_b64 s[16:17], s[24:25]
	v_lshl_add_u64 v[20:21], s[14:15], 0, v[18:19]
	v_lshl_add_u64 v[18:19], s[16:17], 0, v[18:19]
	v_lshlrev_b32_e32 v78, 2, v112
	v_mov_b32_e32 v79, v111
	s_mov_b64 s[20:21], s[28:29]
	v_lshl_add_u64 v[20:21], v[20:21], 0, v[78:79]
	v_lshl_add_u64 v[18:19], v[18:19], 0, v[78:79]
	s_lshl_b32 s1, s0, 11
	global_load_dwordx4 v[58:61], v[20:21], off
	global_load_dwordx4 v[50:53], v[20:21], off offset:64
	global_load_dwordx4 v[62:65], v[18:19], off
	global_load_dwordx4 v[54:57], v[18:19], off offset:64
	global_load_dwordx4 v[42:45], v[20:21], off offset:128
	global_load_dwordx4 v[34:37], v[20:21], off offset:192
	global_load_dwordx4 v[46:49], v[18:19], off offset:128
	global_load_dwordx4 v[38:41], v[18:19], off offset:192
	s_add_u32 s8, s20, s1
	v_lshlrev_b32_e32 v18, 2, v149
	s_mov_b64 s[18:19], s[26:27]
	s_addc_u32 s9, s21, 0
	v_lshl_or_b32 v18, v145, 9, v18
	s_lshl_b32 s1, s0, 4
	s_lshl_b32 s2, s0, 6
	global_load_dword v191, v18, s[8:9]
	global_load_dword v161, v18, s[8:9] offset:64
	global_load_dword v193, v18, s[8:9] offset:128
	global_load_dword v190, v18, s[8:9] offset:192
	global_load_dword v195, v18, s[8:9] offset:256
	global_load_dword v192, v18, s[8:9] offset:320
	global_load_dword v196, v18, s[8:9] offset:384
	global_load_dword v194, v18, s[8:9] offset:448
	s_add_u32 s8, s18, s2
	s_mov_b64 s[22:23], s[30:31]
	s_addc_u32 s9, s19, 0
	s_lshl_b32 s2, s0, 7
	s_add_u32 s10, s22, s2
	s_movk_i32 s2, 0x210
	v_mul_lo_u32 v102, v144, s2
	v_add3_u32 v163, 0, v102, v153
	s_addc_u32 s11, s23, 0
	global_load_dwordx4 v[18:21], v78, s[8:9]
	global_load_dwordx4 v[22:25], v78, s[10:11]
	global_load_dwordx4 v[26:29], v78, s[10:11] offset:64
	v_readlane_b32 s36, v249, 0
	s_and_b32 s36, s36, 63
	s_lshl_b32 s36, s36, 9
	s_add_u32 s36, s36, 0x2308000
	s_add_u32 s36, s94, s36
	s_addc_u32 s37, s95, 0
	s_add_u32 s38, s36, 0x8000
	s_addc_u32 s39, s37, 0
	v_lshlrev_b32_e32 v238, 3, v162
	s_nop 1
	global_load_dwordx2 v[234:235], v238, s[36:37]
	global_load_dwordx2 v[236:237], v238, s[38:39]
	s_waitcnt lgkmcnt(0)
	s_barrier
; #define LAS __attribute__((address_space(3)))
; #define S5_UPDATE(K, hre, him, xq) do { const v2u xb_ = (xq); \
;     _Pragma("unroll") for (int j = 0; j < 4; ++j) { const f32x4 cre_ = K.ar[j] * hre[j] - K.ai[j] * him[j], cim_ = K.ar[j] * him[j] + K.ai[j] * hre[j]; \
;         hre[j] = MFMA16K16(K.Bf[2 * j], xb_, cre_); him[j] = MFMA16K16(K.Bf[2 * j + 1], xb_, cim_); } } while (0)
; __device__ __forceinline__ void s5_prompt_task(const Args& a, const Ctx& C, int b, int g, v4u (&xv)[8]) {
;     ...
;     const int chunk = 16 * w + n;
;     f32x4 hre[4], him[4];
; #pragma unroll
;     for (int j = 0; j < 4; ++j) { hre[j] = (f32x4){0.f, 0.f, 0.f, 0.f}; him[j] = (f32x4){0.f, 0.f, 0.f, 0.f}; }
;     const LAS unsigned char* xsl = XS + chunk * 528 + q * 8;
;     for (int t = 0; t < 16; ++t) { const v2u xq = *(const LAS v2u*)(xsl + t * 32); S5_UPDATE(K, hre, him, xq); }
	ds_read2_b64 v[104:107], v163 offset1:4
	s_waitcnt vmcnt(32)
	v_mov_b32_e32 v78, v30
	v_mov_b32_e32 v79, v32
	v_mov_b32_e32 v80, v2
	v_mov_b32_e32 v81, v4
	v_pk_mul_f32 v[86:87], v[78:79], 0 op_sel_hi:[1,0]
	v_pk_mul_f32 v[90:91], v[80:81], 0 op_sel_hi:[1,0]
	v_xor_b32_e32 v83, 0x80000000, v33
	v_xor_b32_e32 v82, 0x80000000, v31
	v_xor_b32_e32 v85, 0x80000000, v5
	v_xor_b32_e32 v84, 0x80000000, v3
	v_mov_b32_e32 v118, v3
	v_pk_fma_f32 v[82:83], v[82:83], 0, v[86:87] op_sel_hi:[1,0,1]
	v_pk_fma_f32 v[84:85], v[84:85], 0, v[90:91] op_sel_hi:[1,0,1]
	v_mov_b32_e32 v88, v31
	v_mov_b32_e32 v89, v33
	v_mov_b32_e32 v119, v5
	s_waitcnt vmcnt(31) lgkmcnt(0)
	v_mfma_f32_16x16x16_bf16 v[138:141], v[114:115], v[104:105], v[82:85]
	s_nop 2
	v_fma_f32 v82, v88, 0, v86
	v_fma_f32 v83, v89, 0, v87
	v_pk_fma_f32 v[84:85], v[118:119], 0, v[90:91] op_sel_hi:[1,0,1]
	v_mov_b32_e32 v86, v6
	v_mov_b32_e32 v87, v8
	s_waitcnt vmcnt(30)
	v_mfma_f32_16x16x16_bf16 v[146:149], v[116:117], v[104:105], v[82:85]
	v_mul_f32_e64 v94, v86, 0
	v_mul_f32_e64 v95, v87, 0
	v_xor_b32_e32 v91, 0x80000000, v9
	v_xor_b32_e32 v90, 0x80000000, v7
	s_waitcnt vmcnt(29)
	v_mov_b32_e32 v82, v70
	v_mov_b32_e32 v83, v72
	v_mov_b32_e32 v120, v7
	v_pk_mul_f32 v[84:85], v[82:83], 0 op_sel_hi:[1,0]
	v_pk_fma_f32 v[92:93], v[90:91], 0, v[94:95] op_sel_hi:[1,0,1]
	v_xor_b32_e32 v91, 0x80000000, v73
	v_xor_b32_e32 v90, 0x80000000, v71
	v_mov_b32_e32 v121, v9
	v_pk_fma_f32 v[90:91], v[90:91], 0, v[84:85] op_sel_hi:[1,0,1]
	v_pk_fma_f32 v[98:99], v[120:121], 0, v[94:95] op_sel_hi:[1,0,1]
	v_mov_b32_e32 v94, v71
	v_mov_b32_e32 v95, v73
	s_waitcnt vmcnt(26)
	v_mfma_f32_16x16x16_bf16 v[150:153], v[126:127], v[104:105], v[90:93]
	v_fma_f32 v96, v94, 0, v84
	v_fma_f32 v97, v95, 0, v85
	v_mov_b32_e32 v84, v74
	v_mov_b32_e32 v85, v76
	v_mov_b32_e32 v92, v10
	v_mov_b32_e32 v93, v12
	s_waitcnt vmcnt(25)
	v_mfma_f32_16x16x16_bf16 v[154:157], v[128:129], v[104:105], v[96:99]
	v_mul_f32_e64 v100, v92, 0
	v_mul_f32_e64 v101, v93, 0
	v_pk_mul_f32 v[90:91], v[84:85], 0 op_sel_hi:[1,0]
	v_mov_b32_e32 v122, v11
	v_xor_b32_e32 v97, 0x80000000, v13
	v_xor_b32_e32 v96, 0x80000000, v11
	v_pk_fma_f32 v[98:99], v[96:97], 0, v[100:101] op_sel_hi:[1,0,1]
	v_xor_b32_e32 v97, 0x80000000, v77
	v_xor_b32_e32 v96, 0x80000000, v75
	v_pk_fma_f32 v[96:97], v[96:97], 0, v[90:91] op_sel_hi:[1,0,1]
	v_mov_b32_e32 v123, v13
	v_pk_fma_f32 v[166:167], v[122:123], 0, v[100:101] op_sel_hi:[1,0,1]
	s_waitcnt vmcnt(24)
	v_mfma_f32_16x16x16_bf16 v[168:171], v[130:131], v[104:105], v[96:99]
	v_xor_b32_e32 v143, 0x80000000, v17
	v_xor_b32_e32 v142, 0x80000000, v15
	v_mov_b32_e32 v124, v15
	v_mov_b32_e32 v98, v75
	v_mov_b32_e32 v99, v77
	v_mov_b32_e32 v96, v14
	v_mov_b32_e32 v97, v16
	v_pk_fma_f32 v[164:165], v[98:99], 0, v[90:91] op_sel_hi:[1,0,1]
	v_mov_b32_e32 v90, v66
	v_mov_b32_e32 v91, v68
	v_pk_mul_f32 v[100:101], v[96:97], 0 op_sel_hi:[1,0]
	v_pk_mul_f32 v[108:109], v[90:91], 0 op_sel_hi:[1,0]
	v_pk_fma_f32 v[174:175], v[142:143], 0, v[100:101] op_sel_hi:[1,0,1]
	v_xor_b32_e32 v143, 0x80000000, v69
	v_xor_b32_e32 v142, 0x80000000, v67
	v_mov_b32_e32 v125, v17
	v_pk_fma_f32 v[172:173], v[142:143], 0, v[108:109] op_sel_hi:[1,0,1]
	v_pk_fma_f32 v[176:177], v[124:125], 0, v[100:101] op_sel_hi:[1,0,1]
	v_mov_b32_e32 v100, v67
	v_mov_b32_e32 v101, v69
	s_waitcnt vmcnt(22)
	v_mfma_f32_16x16x16_bf16 v[178:181], v[134:135], v[104:105], v[172:175]
	s_add_i32 s8, 0, 0x10800
	v_add_u32_e32 v3, s8, v102
	v_lshlrev_b32_e32 v7, 5, v145
	v_pk_fma_f32 v[174:175], v[100:101], 0, v[108:109] op_sel_hi:[1,0,1]
	v_mfma_f32_16x16x16_bf16 v[164:167], v[132:133], v[104:105], v[164:167]
	v_mul_f32_e64 v108, v88, v146
	v_mul_f32_e64 v109, v89, v147
	v_add_u32_e32 v3, v3, v7
	v_pk_fma_f32 v[182:183], v[78:79], v[138:139], v[108:109] neg_lo:[0,0,1] neg_hi:[0,0,1]
	s_waitcnt vmcnt(21)
	v_mfma_f32_16x16x16_bf16 v[172:175], v[136:137], v[104:105], v[174:177]
	v_mul_f32_e64 v104, v118, v148
	v_mul_f32_e64 v105, v119, v149
	v_pk_mul_f32 v[108:109], v[78:79], v[146:147]
	v_pk_fma_f32 v[184:185], v[80:81], v[140:141], v[104:105] neg_lo:[0,0,1] neg_hi:[0,0,1]
	v_pk_mul_f32 v[104:105], v[80:81], v[148:149]
	v_pk_fma_f32 v[138:139], v[88:89], v[138:139], v[108:109]
	v_pk_fma_f32 v[140:141], v[118:119], v[140:141], v[104:105]
	v_pk_mul_f32 v[104:105], v[120:121], v[156:157]
	v_pk_mul_f32 v[108:109], v[94:95], v[154:155]
	v_pk_fma_f32 v[148:149], v[86:87], v[152:153], v[104:105] neg_lo:[0,0,1] neg_hi:[0,0,1]
	v_pk_fma_f32 v[146:147], v[82:83], v[150:151], v[108:109] neg_lo:[0,0,1] neg_hi:[0,0,1]
	v_pk_mul_f32 v[104:105], v[86:87], v[156:157]
	v_pk_mul_f32 v[108:109], v[82:83], v[154:155]
	v_pk_fma_f32 v[152:153], v[120:121], v[152:153], v[104:105]
	v_pk_fma_f32 v[150:151], v[94:95], v[150:151], v[108:109]
	v_pk_mul_f32 v[104:105], v[122:123], v[166:167]
	v_pk_mul_f32 v[108:109], v[98:99], v[164:165]
	v_pk_fma_f32 v[156:157], v[92:93], v[170:171], v[104:105] neg_lo:[0,0,1] neg_hi:[0,0,1]
	v_pk_fma_f32 v[154:155], v[84:85], v[168:169], v[108:109] neg_lo:[0,0,1] neg_hi:[0,0,1]
	v_pk_mul_f32 v[104:105], v[92:93], v[166:167]
	v_pk_mul_f32 v[108:109], v[84:85], v[164:165]
	v_pk_fma_f32 v[166:167], v[122:123], v[170:171], v[104:105]
	v_pk_fma_f32 v[164:165], v[98:99], v[168:169], v[108:109]
	v_pk_mul_f32 v[104:105], v[124:125], v[174:175]
	v_pk_mul_f32 v[108:109], v[100:101], v[172:173]
	v_pk_fma_f32 v[170:171], v[96:97], v[180:181], v[104:105] neg_lo:[0,0,1] neg_hi:[0,0,1]
	v_pk_fma_f32 v[168:169], v[90:91], v[178:179], v[108:109] neg_lo:[0,0,1] neg_hi:[0,0,1]
	v_pk_mul_f32 v[104:105], v[96:97], v[174:175]
	v_pk_mul_f32 v[108:109], v[90:91], v[172:173]
	v_mfma_f32_16x16x16_bf16 v[138:141], v[116:117], v[106:107], v[138:141]
	v_fma_f32 v174, v124, v180, v104
	v_fma_f32 v175, v125, v181, v105
	v_pk_fma_f32 v[172:173], v[100:101], v[178:179], v[108:109]
	s_add_u32 s4, s94, s4
	v_mfma_f32_16x16x16_bf16 v[182:185], v[114:115], v[106:107], v[182:185]
	s_addc_u32 s5, s95, s5
	s_nop 1
	v_pk_mul_f32 v[108:109], v[118:119], v[140:141]
	v_pk_mul_f32 v[142:143], v[88:89], v[138:139]
	v_mfma_f32_16x16x16_bf16 v[146:149], v[126:127], v[106:107], v[146:149]
	v_mul_f32_e64 v138, v78, v138
	v_mul_f32_e64 v139, v79, v139
	v_pk_fma_f32 v[178:179], v[80:81], v[184:185], v[108:109] neg_lo:[0,0,1] neg_hi:[0,0,1]
	v_pk_fma_f32 v[176:177], v[78:79], v[182:183], v[142:143] neg_lo:[0,0,1] neg_hi:[0,0,1]
	v_mfma_f32_16x16x16_bf16 v[150:153], v[128:129], v[106:107], v[150:153]
	v_mul_f32_e64 v108, v80, v140
	v_mul_f32_e64 v109, v81, v141
	v_lshlrev_b32_e32 v7, 4, v144
	s_mov_b32 s2, 0x2308000
	v_mfma_f32_16x16x16_bf16 v[154:157], v[130:131], v[106:107], v[154:157]
	v_mov_b32_e32 v160, v111
	v_mfma_f32_16x16x16_bf16 v[164:167], v[132:133], v[106:107], v[164:167]
	v_mfma_f32_16x16x16_bf16 v[168:171], v[134:135], v[106:107], v[168:171]
	v_mfma_f32_16x16x16_bf16 v[104:107], v[136:137], v[106:107], v[172:175]
	s_nop 2
	ds_read2_b64 v[172:175], v163 offset0:8 offset1:12
	s_waitcnt lgkmcnt(0)
; #define LAS __attribute__((address_space(3)))
; #define S5_UPDATE(K, hre, him, xq) do { const v2u xb_ = (xq); \
;     _Pragma("unroll") for (int j = 0; j < 4; ++j) { const f32x4 cre_ = K.ar[j] * hre[j] - K.ai[j] * him[j], cim_ = K.ar[j] * him[j] + K.ai[j] * hre[j]; \
;         hre[j] = MFMA16K16(K.Bf[2 * j], xb_, cre_); him[j] = MFMA16K16(K.Bf[2 * j + 1], xb_, cim_); } } while (0)
; __device__ __forceinline__ void s5_prompt_task(const Args& a, const Ctx& C, int b, int g, v4u (&xv)[8]) {
;     ...
;     const int chunk = 16 * w + n;
;     f32x4 hre[4], him[4];
; #pragma unroll
;     for (int j = 0; j < 4; ++j) { hre[j] = (f32x4){0.f, 0.f, 0.f, 0.f}; him[j] = (f32x4){0.f, 0.f, 0.f, 0.f}; }
;     const LAS unsigned char* xsl = XS + chunk * 528 + q * 8;
;     for (int t = 0; t < 16; ++t) { const v2u xq = *(const LAS v2u*)(xsl + t * 32); S5_UPDATE(K, hre, him, xq); }
	v_mfma_f32_16x16x16_bf16 v[140:143], v[114:115], v[172:173], v[176:179]
	s_nop 2
	v_fma_f32 v178, v118, v184, v108
	v_fma_f32 v179, v119, v185, v109
	v_pk_fma_f32 v[176:177], v[88:89], v[182:183], v[138:139]
	v_pk_mul_f32 v[108:109], v[120:121], v[152:153]
	v_pk_mul_f32 v[138:139], v[94:95], v[150:151]
	v_pk_fma_f32 v[182:183], v[86:87], v[148:149], v[108:109] neg_lo:[0,0,1] neg_hi:[0,0,1]
	v_pk_fma_f32 v[180:181], v[82:83], v[146:147], v[138:139] neg_lo:[0,0,1] neg_hi:[0,0,1]
	v_pk_mul_f32 v[108:109], v[86:87], v[152:153]
	v_pk_mul_f32 v[138:139], v[82:83], v[150:151]
	v_mfma_f32_16x16x16_bf16 v[176:179], v[116:117], v[172:173], v[176:179]
	v_fma_f32 v148, v120, v148, v108
	v_fma_f32 v149, v121, v149, v109
	v_pk_fma_f32 v[146:147], v[94:95], v[146:147], v[138:139]
	v_pk_mul_f32 v[108:109], v[122:123], v[166:167]
	v_pk_mul_f32 v[138:139], v[98:99], v[164:165]
	v_pk_fma_f32 v[152:153], v[92:93], v[156:157], v[108:109] neg_lo:[0,0,1] neg_hi:[0,0,1]
	v_pk_fma_f32 v[150:151], v[84:85], v[154:155], v[138:139] neg_lo:[0,0,1] neg_hi:[0,0,1]
	v_pk_mul_f32 v[108:109], v[92:93], v[166:167]
	v_pk_mul_f32 v[138:139], v[84:85], v[164:165]
	v_pk_fma_f32 v[156:157], v[122:123], v[156:157], v[108:109]
	v_pk_fma_f32 v[154:155], v[98:99], v[154:155], v[138:139]
	v_pk_mul_f32 v[108:109], v[124:125], v[106:107]
	v_pk_mul_f32 v[138:139], v[100:101], v[104:105]
	v_mfma_f32_16x16x16_bf16 v[146:149], v[128:129], v[172:173], v[146:149]
	v_fma_f32 v166, v96, v170, -v108
	v_fma_f32 v167, v97, v171, -v109
	v_pk_fma_f32 v[164:165], v[90:91], v[168:169], v[138:139] neg_lo:[0,0,1] neg_hi:[0,0,1]
	v_pk_mul_f32 v[138:139], v[96:97], v[106:107]
	v_pk_mul_f32 v[104:105], v[90:91], v[104:105]
	v_mfma_f32_16x16x16_bf16 v[180:183], v[126:127], v[172:173], v[180:183]
	v_mfma_f32_16x16x16_bf16 v[106:109], v[134:135], v[172:173], v[164:167]
	s_nop 2
	v_fma_f32 v166, v124, v170, v138
	v_fma_f32 v167, v125, v171, v139
	v_pk_fma_f32 v[164:165], v[100:101], v[168:169], v[104:105]
	v_pk_mul_f32 v[104:105], v[118:119], v[178:179]
	v_pk_mul_f32 v[138:139], v[88:89], v[176:177]
	v_mfma_f32_16x16x16_bf16 v[154:157], v[132:133], v[172:173], v[154:157]
	v_fma_f32 v170, v80, v142, -v104
	v_fma_f32 v171, v81, v143, -v105
	v_pk_fma_f32 v[168:169], v[78:79], v[140:141], v[138:139] neg_lo:[0,0,1] neg_hi:[0,0,1]
	v_pk_mul_f32 v[104:105], v[80:81], v[178:179]
	v_pk_mul_f32 v[138:139], v[78:79], v[176:177]
	v_mfma_f32_16x16x16_bf16 v[150:153], v[130:131], v[172:173], v[150:153]
	v_fma_f32 v142, v118, v142, v104
	v_fma_f32 v143, v119, v143, v105
	v_pk_fma_f32 v[140:141], v[88:89], v[140:141], v[138:139]
	v_pk_mul_f32 v[104:105], v[120:121], v[148:149]
	v_mfma_f32_16x16x16_bf16 v[164:167], v[136:137], v[172:173], v[164:167]
	v_fma_f32 v178, v86, v182, -v104
	v_fma_f32 v179, v87, v183, -v105
	v_pk_mul_f32 v[104:105], v[86:87], v[148:149]
	v_mfma_f32_16x16x16_bf16 v[138:141], v[116:117], v[174:175], v[140:143]
	v_fma_f32 v148, v120, v182, v104
	v_fma_f32 v149, v121, v183, v105
	v_pk_mul_f32 v[104:105], v[122:123], v[156:157]
	v_pk_mul_f32 v[142:143], v[94:95], v[146:147]
	v_pk_fma_f32 v[182:183], v[92:93], v[152:153], v[104:105] neg_lo:[0,0,1] neg_hi:[0,0,1]
	v_pk_fma_f32 v[176:177], v[82:83], v[180:181], v[142:143] neg_lo:[0,0,1] neg_hi:[0,0,1]
	v_pk_mul_f32 v[142:143], v[82:83], v[146:147]
	v_pk_mul_f32 v[104:105], v[92:93], v[156:157]
	v_pk_fma_f32 v[146:147], v[94:95], v[180:181], v[142:143]
	v_pk_mul_f32 v[142:143], v[98:99], v[154:155]
	v_mfma_f32_16x16x16_bf16 v[168:171], v[114:115], v[174:175], v[168:171]
	v_fma_f32 v180, v84, v150, -v142
	v_fma_f32 v181, v85, v151, -v143
	v_pk_mul_f32 v[142:143], v[84:85], v[154:155]
	v_pk_fma_f32 v[152:153], v[122:123], v[152:153], v[104:105]
	v_pk_fma_f32 v[150:151], v[98:99], v[150:151], v[142:143]
	v_pk_mul_f32 v[104:105], v[124:125], v[166:167]
	v_pk_mul_f32 v[142:143], v[100:101], v[164:165]
	v_mfma_f32_16x16x16_bf16 v[146:149], v[128:129], v[174:175], v[146:149]
	v_mfma_f32_16x16x16_bf16 v[156:159], v[130:131], v[174:175], v[180:183]
	s_nop 2
	v_fma_f32 v182, v96, v108, -v104
	v_fma_f32 v183, v97, v109, -v105
	v_pk_fma_f32 v[180:181], v[90:91], v[106:107], v[142:143] neg_lo:[0,0,1] neg_hi:[0,0,1]
	v_pk_mul_f32 v[104:105], v[96:97], v[166:167]
	v_pk_mul_f32 v[142:143], v[90:91], v[164:165]
	ds_read2_b64 v[164:167], v163 offset0:16 offset1:20
	v_mfma_f32_16x16x16_bf16 v[176:179], v[126:127], v[174:175], v[176:179]
	v_fma_f32 v108, v124, v108, v104
	v_fma_f32 v109, v125, v109, v105
	v_pk_fma_f32 v[106:107], v[100:101], v[106:107], v[142:143]
	v_pk_mul_f32 v[142:143], v[88:89], v[138:139]
	v_mfma_f32_16x16x16_bf16 v[150:153], v[132:133], v[174:175], v[150:153]
	v_mul_f32_e64 v138, v78, v138
	v_mul_f32_e64 v139, v79, v139
	v_pk_fma_f32 v[172:173], v[78:79], v[168:169], v[142:143] neg_lo:[0,0,1] neg_hi:[0,0,1]
	v_pk_fma_f32 v[168:169], v[88:89], v[168:169], v[138:139]
	v_mfma_f32_16x16x16_bf16 v[104:107], v[136:137], v[174:175], v[106:109]
	v_mul_f32_e64 v138, v94, v146
	v_mul_f32_e64 v139, v95, v147
	s_nop 0
	v_pk_mul_f32 v[108:109], v[118:119], v[140:141]
	v_mfma_f32_16x16x16_bf16 v[180:183], v[134:135], v[174:175], v[180:183]
	v_fma_f32 v174, v80, v170, -v108
	v_fma_f32 v175, v81, v171, -v109
	v_pk_mul_f32 v[108:109], v[80:81], v[140:141]
	s_nop 0
	v_pk_fma_f32 v[170:171], v[118:119], v[170:171], v[108:109]
	v_pk_mul_f32 v[108:109], v[120:121], v[148:149]
	s_waitcnt lgkmcnt(0)
; #define LAS __attribute__((address_space(3)))
; #define S5_UPDATE(K, hre, him, xq) do { const v2u xb_ = (xq); \
;     _Pragma("unroll") for (int j = 0; j < 4; ++j) { const f32x4 cre_ = K.ar[j] * hre[j] - K.ai[j] * him[j], cim_ = K.ar[j] * him[j] + K.ai[j] * hre[j]; \
;         hre[j] = MFMA16K16(K.Bf[2 * j], xb_, cre_); him[j] = MFMA16K16(K.Bf[2 * j + 1], xb_, cim_); } } while (0)
; __device__ __forceinline__ void s5_prompt_task(const Args& a, const Ctx& C, int b, int g, v4u (&xv)[8]) {
;     ...
;     const int chunk = 16 * w + n;
;     f32x4 hre[4], him[4];
; #pragma unroll
;     for (int j = 0; j < 4; ++j) { hre[j] = (f32x4){0.f, 0.f, 0.f, 0.f}; him[j] = (f32x4){0.f, 0.f, 0.f, 0.f}; }
;     const LAS unsigned char* xsl = XS + chunk * 528 + q * 8;
;     for (int t = 0; t < 16; ++t) { const v2u xq = *(const LAS v2u*)(xsl + t * 32); S5_UPDATE(K, hre, him, xq); }
	v_mfma_f32_16x16x16_bf16 v[140:143], v[114:115], v[164:165], v[172:175]
	s_nop 2
	v_fma_f32 v174, v86, v178, -v108
	v_fma_f32 v175, v87, v179, -v109
	v_pk_fma_f32 v[172:173], v[82:83], v[176:177], v[138:139] neg_lo:[0,0,1] neg_hi:[0,0,1]
	v_pk_mul_f32 v[108:109], v[86:87], v[148:149]
	v_pk_mul_f32 v[138:139], v[82:83], v[146:147]
	v_mfma_f32_16x16x16_bf16 v[168:171], v[116:117], v[164:165], v[168:171]
	v_fma_f32 v148, v120, v178, v108
	v_fma_f32 v149, v121, v179, v109
	v_pk_fma_f32 v[146:147], v[94:95], v[176:177], v[138:139]
	v_pk_mul_f32 v[108:109], v[122:123], v[152:153]
	v_pk_mul_f32 v[138:139], v[98:99], v[150:151]
	v_pk_fma_f32 v[178:179], v[92:93], v[158:159], v[108:109] neg_lo:[0,0,1] neg_hi:[0,0,1]
	v_pk_fma_f32 v[176:177], v[84:85], v[156:157], v[138:139] neg_lo:[0,0,1] neg_hi:[0,0,1]
	v_pk_mul_f32 v[108:109], v[92:93], v[152:153]
	v_pk_mul_f32 v[138:139], v[84:85], v[150:151]
	v_pk_fma_f32 v[158:159], v[122:123], v[158:159], v[108:109]
	v_pk_fma_f32 v[156:157], v[98:99], v[156:157], v[138:139]
	v_pk_mul_f32 v[108:109], v[124:125], v[106:107]
	v_pk_mul_f32 v[138:139], v[100:101], v[104:105]
	v_mfma_f32_16x16x16_bf16 v[146:149], v[128:129], v[164:165], v[146:149]
	v_mul_f32_e64 v104, v90, v104
	v_mul_f32_e64 v105, v91, v105
	v_mfma_f32_16x16x16_bf16 v[152:155], v[130:131], v[164:165], v[176:179]
	s_nop 2
	v_fma_f32 v178, v96, v182, -v108
	v_fma_f32 v179, v97, v183, -v109
	v_pk_fma_f32 v[176:177], v[90:91], v[180:181], v[138:139] neg_lo:[0,0,1] neg_hi:[0,0,1]
	v_pk_mul_f32 v[138:139], v[96:97], v[106:107]
	v_mfma_f32_16x16x16_bf16 v[172:175], v[126:127], v[164:165], v[172:175]
	v_mfma_f32_16x16x16_bf16 v[106:109], v[134:135], v[164:165], v[176:179]
	s_nop 2
	v_fma_f32 v178, v124, v182, v138
	v_fma_f32 v179, v125, v183, v139
	v_pk_fma_f32 v[176:177], v[100:101], v[180:181], v[104:105]
	v_pk_mul_f32 v[104:105], v[118:119], v[170:171]
	v_pk_mul_f32 v[138:139], v[88:89], v[168:169]
	v_mfma_f32_16x16x16_bf16 v[156:159], v[132:133], v[164:165], v[156:159]
	v_fma_f32 v182, v80, v142, -v104
	v_fma_f32 v183, v81, v143, -v105
	v_pk_fma_f32 v[180:181], v[78:79], v[140:141], v[138:139] neg_lo:[0,0,1] neg_hi:[0,0,1]
	v_pk_mul_f32 v[104:105], v[80:81], v[170:171]
	v_pk_mul_f32 v[138:139], v[78:79], v[168:169]
	v_pk_fma_f32 v[142:143], v[118:119], v[142:143], v[104:105]
	v_pk_fma_f32 v[140:141], v[88:89], v[140:141], v[138:139]
	v_mfma_f32_16x16x16_bf16 v[176:179], v[136:137], v[164:165], v[176:179]
	v_mul_f32_e64 v104, v120, v148
	v_mul_f32_e64 v105, v121, v149
	v_pk_fma_f32 v[170:171], v[86:87], v[174:175], v[104:105] neg_lo:[0,0,1] neg_hi:[0,0,1]
	v_mfma_f32_16x16x16_bf16 v[138:141], v[116:117], v[166:167], v[140:143]
	v_mul_f32_e64 v104, v86, v148
	v_mul_f32_e64 v105, v87, v149
	s_nop 0
	v_pk_mul_f32 v[142:143], v[94:95], v[146:147]
	v_mfma_f32_16x16x16_bf16 v[180:183], v[114:115], v[166:167], v[180:183]
	v_fma_f32 v168, v82, v172, -v142
	v_fma_f32 v169, v83, v173, -v143
	v_pk_mul_f32 v[142:143], v[82:83], v[146:147]
	s_nop 0
	v_mfma_f32_16x16x16_bf16 v[148:151], v[126:127], v[166:167], v[168:171]
	s_nop 2
	v_fma_f32 v170, v120, v174, v104
	v_fma_f32 v171, v121, v175, v105
	v_pk_fma_f32 v[168:169], v[94:95], v[172:173], v[142:143]
	v_pk_mul_f32 v[104:105], v[122:123], v[158:159]
	v_pk_mul_f32 v[142:143], v[98:99], v[156:157]
	v_pk_fma_f32 v[174:175], v[92:93], v[154:155], v[104:105] neg_lo:[0,0,1] neg_hi:[0,0,1]
	v_pk_fma_f32 v[172:173], v[84:85], v[152:153], v[142:143] neg_lo:[0,0,1] neg_hi:[0,0,1]
	v_pk_mul_f32 v[104:105], v[92:93], v[158:159]
	v_pk_mul_f32 v[142:143], v[84:85], v[156:157]
	v_pk_fma_f32 v[154:155], v[122:123], v[154:155], v[104:105]
	v_pk_fma_f32 v[152:153], v[98:99], v[152:153], v[142:143]
	v_pk_mul_f32 v[104:105], v[124:125], v[178:179]
	v_pk_mul_f32 v[142:143], v[100:101], v[176:177]
	v_pk_fma_f32 v[158:159], v[96:97], v[108:109], v[104:105] neg_lo:[0,0,1] neg_hi:[0,0,1]
	v_pk_fma_f32 v[156:157], v[90:91], v[106:107], v[142:143] neg_lo:[0,0,1] neg_hi:[0,0,1]
	v_pk_mul_f32 v[104:105], v[96:97], v[178:179]
	v_pk_mul_f32 v[142:143], v[90:91], v[176:177]
	v_pk_fma_f32 v[108:109], v[124:125], v[108:109], v[104:105]
	v_pk_fma_f32 v[106:107], v[100:101], v[106:107], v[142:143]
	v_mfma_f32_16x16x16_bf16 v[168:171], v[128:129], v[166:167], v[168:171]
	v_mul_f32_e64 v142, v88, v138
	v_mul_f32_e64 v143, v89, v139
	v_pk_mul_f32 v[138:139], v[78:79], v[138:139]
	v_pk_fma_f32 v[176:177], v[78:79], v[180:181], v[142:143] neg_lo:[0,0,1] neg_hi:[0,0,1]
	v_mfma_f32_16x16x16_bf16 v[172:175], v[130:131], v[166:167], v[172:175]
	v_mfma_f32_16x16x16_bf16 v[152:155], v[132:133], v[166:167], v[152:155]
	v_mfma_f32_16x16x16_bf16 v[156:159], v[134:135], v[166:167], v[156:159]
	v_mfma_f32_16x16x16_bf16 v[104:107], v[136:137], v[166:167], v[106:109]
	ds_read2_b64 v[164:167], v163 offset0:24 offset1:28
	s_nop 1
	v_pk_mul_f32 v[108:109], v[118:119], v[140:141]
	s_nop 0
	v_pk_fma_f32 v[178:179], v[80:81], v[182:183], v[108:109] neg_lo:[0,0,1] neg_hi:[0,0,1]
	v_pk_mul_f32 v[108:109], v[80:81], v[140:141]
	s_waitcnt lgkmcnt(0)
; #define LAS __attribute__((address_space(3)))
; #define S5_UPDATE(K, hre, him, xq) do { const v2u xb_ = (xq); \
;     _Pragma("unroll") for (int j = 0; j < 4; ++j) { const f32x4 cre_ = K.ar[j] * hre[j] - K.ai[j] * him[j], cim_ = K.ar[j] * him[j] + K.ai[j] * hre[j]; \
;         hre[j] = MFMA16K16(K.Bf[2 * j], xb_, cre_); him[j] = MFMA16K16(K.Bf[2 * j + 1], xb_, cim_); } } while (0)
; __device__ __forceinline__ void s5_prompt_task(const Args& a, const Ctx& C, int b, int g, v4u (&xv)[8]) {
;     ...
;     const int chunk = 16 * w + n;
;     f32x4 hre[4], him[4];
; #pragma unroll
;     for (int j = 0; j < 4; ++j) { hre[j] = (f32x4){0.f, 0.f, 0.f, 0.f}; him[j] = (f32x4){0.f, 0.f, 0.f, 0.f}; }
;     const LAS unsigned char* xsl = XS + chunk * 528 + q * 8;
;     for (int t = 0; t < 16; ++t) { const v2u xq = *(const LAS v2u*)(xsl + t * 32); S5_UPDATE(K, hre, him, xq); }
	v_mfma_f32_16x16x16_bf16 v[140:143], v[114:115], v[164:165], v[176:179]
	s_nop 2
	v_fma_f32 v176, v88, v180, v138
	v_fma_f32 v177, v89, v181, v139
	v_pk_mul_f32 v[138:139], v[94:95], v[168:169]
	v_pk_fma_f32 v[178:179], v[118:119], v[182:183], v[108:109]
	v_pk_mul_f32 v[108:109], v[120:121], v[170:171]
	v_pk_fma_f32 v[180:181], v[82:83], v[148:149], v[138:139] neg_lo:[0,0,1] neg_hi:[0,0,1]
	v_pk_mul_f32 v[138:139], v[82:83], v[168:169]
	v_mfma_f32_16x16x16_bf16 v[176:179], v[116:117], v[164:165], v[176:179]
	v_fma_f32 v182, v86, v150, -v108
	v_fma_f32 v183, v87, v151, -v109
	v_pk_mul_f32 v[108:109], v[86:87], v[170:171]
	v_pk_fma_f32 v[148:149], v[94:95], v[148:149], v[138:139]
	v_pk_mul_f32 v[138:139], v[98:99], v[152:153]
	v_pk_fma_f32 v[150:151], v[120:121], v[150:151], v[108:109]
	v_pk_mul_f32 v[108:109], v[122:123], v[154:155]
	v_pk_fma_f32 v[168:169], v[84:85], v[172:173], v[138:139] neg_lo:[0,0,1] neg_hi:[0,0,1]
	v_pk_mul_f32 v[138:139], v[84:85], v[152:153]
	v_mfma_f32_16x16x16_bf16 v[146:149], v[128:129], v[164:165], v[148:151]
	v_fma_f32 v170, v92, v174, -v108
	v_fma_f32 v171, v93, v175, -v109
	v_pk_mul_f32 v[108:109], v[92:93], v[154:155]
	v_pk_fma_f32 v[150:151], v[98:99], v[172:173], v[138:139]
	v_pk_mul_f32 v[138:139], v[100:101], v[104:105]
	v_pk_fma_f32 v[152:153], v[122:123], v[174:175], v[108:109]
	v_pk_mul_f32 v[108:109], v[124:125], v[106:107]
	v_pk_fma_f32 v[172:173], v[90:91], v[156:157], v[138:139] neg_lo:[0,0,1] neg_hi:[0,0,1]
	v_pk_mul_f32 v[138:139], v[96:97], v[106:107]
	v_pk_mul_f32 v[104:105], v[90:91], v[104:105]
	v_mfma_f32_16x16x16_bf16 v[180:183], v[126:127], v[164:165], v[180:183]
	v_fma_f32 v174, v96, v158, -v108
	v_fma_f32 v175, v97, v159, -v109
	v_pk_fma_f32 v[158:159], v[124:125], v[158:159], v[138:139]
	v_pk_fma_f32 v[156:157], v[100:101], v[156:157], v[104:105]
	v_pk_mul_f32 v[104:105], v[118:119], v[178:179]
	v_pk_mul_f32 v[138:139], v[88:89], v[176:177]
	v_mfma_f32_16x16x16_bf16 v[150:153], v[132:133], v[164:165], v[150:153]
	v_mfma_f32_16x16x16_bf16 v[106:109], v[134:135], v[164:165], v[172:175]
	s_nop 2
	v_fma_f32 v174, v80, v142, -v104
	v_fma_f32 v175, v81, v143, -v105
	v_pk_fma_f32 v[172:173], v[78:79], v[140:141], v[138:139] neg_lo:[0,0,1] neg_hi:[0,0,1]
	v_pk_mul_f32 v[104:105], v[80:81], v[178:179]
	v_pk_mul_f32 v[138:139], v[78:79], v[176:177]
	v_mfma_f32_16x16x16_bf16 v[168:171], v[130:131], v[164:165], v[168:171]
	v_fma_f32 v142, v118, v142, v104
	v_fma_f32 v143, v119, v143, v105
	v_pk_fma_f32 v[140:141], v[88:89], v[140:141], v[138:139]
	v_pk_mul_f32 v[104:105], v[120:121], v[148:149]
	v_mfma_f32_16x16x16_bf16 v[154:157], v[136:137], v[164:165], v[156:159]
	v_fma_f32 v178, v86, v182, -v104
	v_fma_f32 v179, v87, v183, -v105
	v_pk_mul_f32 v[104:105], v[86:87], v[148:149]
	v_mfma_f32_16x16x16_bf16 v[138:141], v[116:117], v[166:167], v[140:143]
	v_fma_f32 v148, v120, v182, v104
	v_fma_f32 v149, v121, v183, v105
	v_pk_mul_f32 v[104:105], v[122:123], v[152:153]
	v_pk_mul_f32 v[142:143], v[94:95], v[146:147]
	v_pk_fma_f32 v[182:183], v[92:93], v[170:171], v[104:105] neg_lo:[0,0,1] neg_hi:[0,0,1]
	v_pk_fma_f32 v[176:177], v[82:83], v[180:181], v[142:143] neg_lo:[0,0,1] neg_hi:[0,0,1]
	v_pk_mul_f32 v[142:143], v[82:83], v[146:147]
	v_pk_mul_f32 v[104:105], v[92:93], v[152:153]
	v_pk_fma_f32 v[146:147], v[94:95], v[180:181], v[142:143]
	v_pk_mul_f32 v[142:143], v[98:99], v[150:151]
	v_pk_fma_f32 v[152:153], v[122:123], v[170:171], v[104:105]
	v_pk_fma_f32 v[180:181], v[84:85], v[168:169], v[142:143] neg_lo:[0,0,1] neg_hi:[0,0,1]
	v_pk_mul_f32 v[142:143], v[84:85], v[150:151]
	v_pk_mul_f32 v[104:105], v[124:125], v[156:157]
	v_pk_fma_f32 v[150:151], v[98:99], v[168:169], v[142:143]
	v_pk_mul_f32 v[142:143], v[100:101], v[154:155]
	v_pk_fma_f32 v[170:171], v[96:97], v[108:109], v[104:105] neg_lo:[0,0,1] neg_hi:[0,0,1]
	v_pk_fma_f32 v[168:169], v[90:91], v[106:107], v[142:143] neg_lo:[0,0,1] neg_hi:[0,0,1]
	v_pk_mul_f32 v[104:105], v[96:97], v[156:157]
	v_pk_mul_f32 v[142:143], v[90:91], v[154:155]
	v_pk_fma_f32 v[108:109], v[124:125], v[108:109], v[104:105]
	v_pk_fma_f32 v[106:107], v[100:101], v[106:107], v[142:143]
	v_mfma_f32_16x16x16_bf16 v[172:175], v[114:115], v[166:167], v[172:175]
	v_mul_f32_e64 v142, v88, v138
	v_mul_f32_e64 v143, v89, v139
	v_pk_mul_f32 v[138:139], v[78:79], v[138:139]
	v_mfma_f32_16x16x16_bf16 v[176:179], v[126:127], v[166:167], v[176:179]
	v_mfma_f32_16x16x16_bf16 v[146:149], v[128:129], v[166:167], v[146:149]
	v_mfma_f32_16x16x16_bf16 v[180:183], v[130:131], v[166:167], v[180:183]
	v_mfma_f32_16x16x16_bf16 v[150:153], v[132:133], v[166:167], v[150:153]
	v_mfma_f32_16x16x16_bf16 v[156:159], v[134:135], v[166:167], v[168:171]
	v_mfma_f32_16x16x16_bf16 v[104:107], v[136:137], v[166:167], v[106:109]
	ds_read2_b64 v[164:167], v163 offset0:32 offset1:36
	s_nop 0
	v_pk_fma_f32 v[168:169], v[78:79], v[172:173], v[142:143] neg_lo:[0,0,1] neg_hi:[0,0,1]
	v_pk_mul_f32 v[108:109], v[118:119], v[140:141]
	s_nop 0
	v_pk_fma_f32 v[170:171], v[80:81], v[174:175], v[108:109] neg_lo:[0,0,1] neg_hi:[0,0,1]
	v_pk_mul_f32 v[108:109], v[80:81], v[140:141]
	s_waitcnt lgkmcnt(0)
; #define LAS __attribute__((address_space(3)))
; #define S5_UPDATE(K, hre, him, xq) do { const v2u xb_ = (xq); \
;     _Pragma("unroll") for (int j = 0; j < 4; ++j) { const f32x4 cre_ = K.ar[j] * hre[j] - K.ai[j] * him[j], cim_ = K.ar[j] * him[j] + K.ai[j] * hre[j]; \
;         hre[j] = MFMA16K16(K.Bf[2 * j], xb_, cre_); him[j] = MFMA16K16(K.Bf[2 * j + 1], xb_, cim_); } } while (0)
; __device__ __forceinline__ void s5_prompt_task(const Args& a, const Ctx& C, int b, int g, v4u (&xv)[8]) {
;     ...
;     const int chunk = 16 * w + n;
;     f32x4 hre[4], him[4];
; #pragma unroll
;     for (int j = 0; j < 4; ++j) { hre[j] = (f32x4){0.f, 0.f, 0.f, 0.f}; him[j] = (f32x4){0.f, 0.f, 0.f, 0.f}; }
;     const LAS unsigned char* xsl = XS + chunk * 528 + q * 8;
;     for (int t = 0; t < 16; ++t) { const v2u xq = *(const LAS v2u*)(xsl + t * 32); S5_UPDATE(K, hre, him, xq); }
	v_mfma_f32_16x16x16_bf16 v[140:143], v[114:115], v[164:165], v[168:171]
	s_nop 2
	v_fma_f32 v170, v118, v174, v108
	v_fma_f32 v171, v119, v175, v109
	v_pk_fma_f32 v[168:169], v[88:89], v[172:173], v[138:139]
	v_pk_mul_f32 v[108:109], v[120:121], v[148:149]
	v_pk_mul_f32 v[138:139], v[94:95], v[146:147]
	v_pk_fma_f32 v[174:175], v[86:87], v[178:179], v[108:109] neg_lo:[0,0,1] neg_hi:[0,0,1]
	v_pk_fma_f32 v[172:173], v[82:83], v[176:177], v[138:139] neg_lo:[0,0,1] neg_hi:[0,0,1]
	v_pk_mul_f32 v[108:109], v[86:87], v[148:149]
	v_pk_mul_f32 v[138:139], v[82:83], v[146:147]
	v_mfma_f32_16x16x16_bf16 v[168:171], v[116:117], v[164:165], v[168:171]
	v_fma_f32 v148, v120, v178, v108
	v_fma_f32 v149, v121, v179, v109
	v_pk_fma_f32 v[146:147], v[94:95], v[176:177], v[138:139]
	v_pk_mul_f32 v[108:109], v[122:123], v[152:153]
	v_pk_mul_f32 v[138:139], v[98:99], v[150:151]
	v_pk_fma_f32 v[178:179], v[92:93], v[182:183], v[108:109] neg_lo:[0,0,1] neg_hi:[0,0,1]
	v_pk_fma_f32 v[176:177], v[84:85], v[180:181], v[138:139] neg_lo:[0,0,1] neg_hi:[0,0,1]
	v_pk_mul_f32 v[138:139], v[84:85], v[150:151]
	v_pk_mul_f32 v[108:109], v[92:93], v[152:153]
	v_mfma_f32_16x16x16_bf16 v[152:155], v[130:131], v[164:165], v[176:179]
	s_nop 2
	v_fma_f32 v176, v98, v180, v138
	v_fma_f32 v177, v99, v181, v139
	v_pk_mul_f32 v[138:139], v[100:101], v[104:105]
	v_mfma_f32_16x16x16_bf16 v[146:149], v[128:129], v[164:165], v[146:149]
	v_fma_f32 v178, v122, v182, v108
	v_fma_f32 v179, v123, v183, v109
	v_pk_mul_f32 v[108:109], v[124:125], v[106:107]
	v_pk_fma_f32 v[180:181], v[90:91], v[156:157], v[138:139] neg_lo:[0,0,1] neg_hi:[0,0,1]
	v_pk_mul_f32 v[138:139], v[96:97], v[106:107]
	v_pk_mul_f32 v[104:105], v[90:91], v[104:105]
	v_mfma_f32_16x16x16_bf16 v[172:175], v[126:127], v[164:165], v[172:175]
	v_fma_f32 v182, v96, v158, -v108
	v_fma_f32 v183, v97, v159, -v109
	v_pk_fma_f32 v[158:159], v[124:125], v[158:159], v[138:139]
	v_pk_fma_f32 v[156:157], v[100:101], v[156:157], v[104:105]
	v_pk_mul_f32 v[104:105], v[118:119], v[170:171]
	v_pk_mul_f32 v[138:139], v[88:89], v[168:169]
	v_mfma_f32_16x16x16_bf16 v[176:179], v[132:133], v[164:165], v[176:179]
	v_mfma_f32_16x16x16_bf16 v[106:109], v[134:135], v[164:165], v[180:183]
	s_nop 2
	v_fma_f32 v182, v80, v142, -v104
	v_fma_f32 v183, v81, v143, -v105
	v_pk_fma_f32 v[180:181], v[78:79], v[140:141], v[138:139] neg_lo:[0,0,1] neg_hi:[0,0,1]
	v_pk_mul_f32 v[104:105], v[80:81], v[170:171]
	v_pk_mul_f32 v[138:139], v[78:79], v[168:169]
	v_pk_fma_f32 v[142:143], v[118:119], v[142:143], v[104:105]
	v_pk_fma_f32 v[140:141], v[88:89], v[140:141], v[138:139]
	v_mfma_f32_16x16x16_bf16 v[156:159], v[136:137], v[164:165], v[156:159]
	v_mul_f32_e64 v104, v120, v148
	v_mul_f32_e64 v105, v121, v149
	v_pk_fma_f32 v[170:171], v[86:87], v[174:175], v[104:105] neg_lo:[0,0,1] neg_hi:[0,0,1]
	v_mfma_f32_16x16x16_bf16 v[138:141], v[116:117], v[166:167], v[140:143]
	v_mul_f32_e64 v104, v86, v148
	v_mul_f32_e64 v105, v87, v149
	s_nop 0
	v_pk_mul_f32 v[142:143], v[94:95], v[146:147]
	v_mfma_f32_16x16x16_bf16 v[180:183], v[114:115], v[166:167], v[180:183]
	v_fma_f32 v168, v82, v172, -v142
	v_fma_f32 v169, v83, v173, -v143
	v_pk_mul_f32 v[142:143], v[82:83], v[146:147]
	s_nop 0
	v_mfma_f32_16x16x16_bf16 v[148:151], v[126:127], v[166:167], v[168:171]
	s_nop 2
	v_fma_f32 v170, v120, v174, v104
	v_fma_f32 v171, v121, v175, v105
	v_pk_fma_f32 v[168:169], v[94:95], v[172:173], v[142:143]
	v_pk_mul_f32 v[104:105], v[122:123], v[178:179]
	v_pk_mul_f32 v[142:143], v[98:99], v[176:177]
	v_pk_fma_f32 v[174:175], v[92:93], v[154:155], v[104:105] neg_lo:[0,0,1] neg_hi:[0,0,1]
	v_pk_fma_f32 v[172:173], v[84:85], v[152:153], v[142:143] neg_lo:[0,0,1] neg_hi:[0,0,1]
	v_pk_mul_f32 v[104:105], v[92:93], v[178:179]
	v_pk_mul_f32 v[142:143], v[84:85], v[176:177]
	v_pk_fma_f32 v[154:155], v[122:123], v[154:155], v[104:105]
	v_pk_fma_f32 v[152:153], v[98:99], v[152:153], v[142:143]
	v_pk_mul_f32 v[104:105], v[124:125], v[158:159]
	v_pk_mul_f32 v[142:143], v[100:101], v[156:157]
	v_pk_fma_f32 v[178:179], v[96:97], v[108:109], v[104:105] neg_lo:[0,0,1] neg_hi:[0,0,1]
	v_pk_fma_f32 v[176:177], v[90:91], v[106:107], v[142:143] neg_lo:[0,0,1] neg_hi:[0,0,1]
	v_pk_mul_f32 v[104:105], v[96:97], v[158:159]
	v_pk_mul_f32 v[142:143], v[90:91], v[156:157]
	ds_read2_b64 v[156:159], v163 offset0:40 offset1:44
	v_mfma_f32_16x16x16_bf16 v[168:171], v[128:129], v[166:167], v[168:171]
	v_fma_f32 v108, v124, v108, v104
	v_fma_f32 v109, v125, v109, v105
	v_pk_fma_f32 v[106:107], v[100:101], v[106:107], v[142:143]
	v_pk_mul_f32 v[142:143], v[88:89], v[138:139]
	v_mfma_f32_16x16x16_bf16 v[152:155], v[132:133], v[166:167], v[152:155]
	v_fma_f32 v164, v78, v180, -v142
	v_fma_f32 v165, v79, v181, -v143
	v_pk_mul_f32 v[138:139], v[78:79], v[138:139]
	v_mfma_f32_16x16x16_bf16 v[104:107], v[136:137], v[166:167], v[106:109]
	s_nop 2
	v_mul_f32_e64 v108, v118, v140
	v_mul_f32_e64 v109, v119, v141
	v_mfma_f32_16x16x16_bf16 v[172:175], v[130:131], v[166:167], v[172:175]
	v_mfma_f32_16x16x16_bf16 v[176:179], v[134:135], v[166:167], v[176:179]
	v_fma_f32 v166, v80, v182, -v108
	v_fma_f32 v167, v81, v183, -v109
	v_pk_mul_f32 v[108:109], v[80:81], v[140:141]
	s_waitcnt lgkmcnt(0)
; #define LAS __attribute__((address_space(3)))
; #define S5_UPDATE(K, hre, him, xq) do { const v2u xb_ = (xq); \
;     _Pragma("unroll") for (int j = 0; j < 4; ++j) { const f32x4 cre_ = K.ar[j] * hre[j] - K.ai[j] * him[j], cim_ = K.ar[j] * him[j] + K.ai[j] * hre[j]; \
;         hre[j] = MFMA16K16(K.Bf[2 * j], xb_, cre_); him[j] = MFMA16K16(K.Bf[2 * j + 1], xb_, cim_); } } while (0)
; __device__ __forceinline__ void s5_prompt_task(const Args& a, const Ctx& C, int b, int g, v4u (&xv)[8]) {
;     ...
;     const int chunk = 16 * w + n;
;     f32x4 hre[4], him[4];
; #pragma unroll
;     for (int j = 0; j < 4; ++j) { hre[j] = (f32x4){0.f, 0.f, 0.f, 0.f}; him[j] = (f32x4){0.f, 0.f, 0.f, 0.f}; }
;     const LAS unsigned char* xsl = XS + chunk * 528 + q * 8;
;     for (int t = 0; t < 16; ++t) { const v2u xq = *(const LAS v2u*)(xsl + t * 32); S5_UPDATE(K, hre, him, xq); }
	v_mfma_f32_16x16x16_bf16 v[140:143], v[114:115], v[156:157], v[164:167]
	s_nop 2
	v_fma_f32 v166, v118, v182, v108
	v_fma_f32 v167, v119, v183, v109
	v_pk_fma_f32 v[164:165], v[88:89], v[180:181], v[138:139]
	v_pk_mul_f32 v[108:109], v[120:121], v[170:171]
	v_pk_mul_f32 v[138:139], v[94:95], v[168:169]
	v_pk_fma_f32 v[182:183], v[86:87], v[150:151], v[108:109] neg_lo:[0,0,1] neg_hi:[0,0,1]
	v_pk_fma_f32 v[180:181], v[82:83], v[148:149], v[138:139] neg_lo:[0,0,1] neg_hi:[0,0,1]
	v_pk_mul_f32 v[108:109], v[86:87], v[170:171]
	v_pk_mul_f32 v[138:139], v[82:83], v[168:169]
	v_mfma_f32_16x16x16_bf16 v[164:167], v[116:117], v[156:157], v[164:167]
	v_fma_f32 v150, v120, v150, v108
	v_fma_f32 v151, v121, v151, v109
	v_pk_fma_f32 v[148:149], v[94:95], v[148:149], v[138:139]
	v_pk_mul_f32 v[108:109], v[122:123], v[154:155]
	v_pk_mul_f32 v[138:139], v[98:99], v[152:153]
	v_pk_fma_f32 v[170:171], v[92:93], v[174:175], v[108:109] neg_lo:[0,0,1] neg_hi:[0,0,1]
	v_pk_fma_f32 v[168:169], v[84:85], v[172:173], v[138:139] neg_lo:[0,0,1] neg_hi:[0,0,1]
	v_pk_mul_f32 v[108:109], v[92:93], v[154:155]
	v_pk_mul_f32 v[138:139], v[84:85], v[152:153]
	v_mfma_f32_16x16x16_bf16 v[146:149], v[128:129], v[156:157], v[148:151]
	v_fma_f32 v152, v122, v174, v108
	v_fma_f32 v153, v123, v175, v109
	v_pk_mul_f32 v[108:109], v[124:125], v[106:107]
	v_pk_fma_f32 v[150:151], v[98:99], v[172:173], v[138:139]
	v_pk_mul_f32 v[138:139], v[100:101], v[104:105]
	v_pk_fma_f32 v[174:175], v[96:97], v[178:179], v[108:109] neg_lo:[0,0,1] neg_hi:[0,0,1]
	v_pk_fma_f32 v[172:173], v[90:91], v[176:177], v[138:139] neg_lo:[0,0,1] neg_hi:[0,0,1]
	v_pk_mul_f32 v[138:139], v[96:97], v[106:107]
	v_pk_mul_f32 v[104:105], v[90:91], v[104:105]
	v_mfma_f32_16x16x16_bf16 v[180:183], v[126:127], v[156:157], v[180:183]
	v_mfma_f32_16x16x16_bf16 v[106:109], v[134:135], v[156:157], v[172:175]
	s_nop 2
	v_fma_f32 v174, v124, v178, v138
	v_fma_f32 v175, v125, v179, v139
	v_pk_fma_f32 v[172:173], v[100:101], v[176:177], v[104:105]
	v_pk_mul_f32 v[104:105], v[118:119], v[166:167]
	v_pk_mul_f32 v[138:139], v[88:89], v[164:165]
	v_mfma_f32_16x16x16_bf16 v[168:171], v[130:131], v[156:157], v[168:171]
	v_mfma_f32_16x16x16_bf16 v[150:153], v[132:133], v[156:157], v[150:153]
	v_mfma_f32_16x16x16_bf16 v[154:157], v[136:137], v[156:157], v[172:175]
	s_nop 2
	v_fma_f32 v174, v80, v142, -v104
	v_fma_f32 v175, v81, v143, -v105
	v_pk_fma_f32 v[172:173], v[78:79], v[140:141], v[138:139] neg_lo:[0,0,1] neg_hi:[0,0,1]
	v_pk_mul_f32 v[104:105], v[80:81], v[166:167]
	v_pk_mul_f32 v[138:139], v[78:79], v[164:165]
	v_pk_fma_f32 v[142:143], v[118:119], v[142:143], v[104:105]
	v_pk_fma_f32 v[140:141], v[88:89], v[140:141], v[138:139]
	v_pk_mul_f32 v[104:105], v[120:121], v[148:149]
	v_mfma_f32_16x16x16_bf16 v[172:175], v[114:115], v[158:159], v[172:175]
	v_fma_f32 v166, v86, v182, -v104
	v_fma_f32 v167, v87, v183, -v105
	v_pk_mul_f32 v[104:105], v[86:87], v[148:149]
	v_mfma_f32_16x16x16_bf16 v[138:141], v[116:117], v[158:159], v[140:143]
	v_fma_f32 v148, v120, v182, v104
	v_fma_f32 v149, v121, v183, v105
	v_pk_mul_f32 v[104:105], v[122:123], v[152:153]
	v_pk_mul_f32 v[142:143], v[94:95], v[146:147]
	v_pk_fma_f32 v[178:179], v[92:93], v[170:171], v[104:105] neg_lo:[0,0,1] neg_hi:[0,0,1]
	v_pk_fma_f32 v[164:165], v[82:83], v[180:181], v[142:143] neg_lo:[0,0,1] neg_hi:[0,0,1]
	v_pk_mul_f32 v[142:143], v[82:83], v[146:147]
	v_pk_mul_f32 v[104:105], v[92:93], v[152:153]
	v_pk_fma_f32 v[146:147], v[94:95], v[180:181], v[142:143]
	v_pk_mul_f32 v[142:143], v[98:99], v[150:151]
	v_pk_fma_f32 v[152:153], v[122:123], v[170:171], v[104:105]
	v_pk_fma_f32 v[176:177], v[84:85], v[168:169], v[142:143] neg_lo:[0,0,1] neg_hi:[0,0,1]
	v_pk_mul_f32 v[142:143], v[84:85], v[150:151]
	v_pk_mul_f32 v[104:105], v[124:125], v[156:157]
	v_pk_fma_f32 v[150:151], v[98:99], v[168:169], v[142:143]
	v_pk_mul_f32 v[142:143], v[100:101], v[154:155]
	v_mfma_f32_16x16x16_bf16 v[146:149], v[128:129], v[158:159], v[146:149]
	v_fma_f32 v170, v96, v108, -v104
	v_fma_f32 v171, v97, v109, -v105
	v_pk_fma_f32 v[168:169], v[90:91], v[106:107], v[142:143] neg_lo:[0,0,1] neg_hi:[0,0,1]
	v_pk_mul_f32 v[104:105], v[96:97], v[156:157]
	v_pk_mul_f32 v[142:143], v[90:91], v[154:155]
	ds_read2_b64 v[154:157], v163 offset0:48 offset1:52
	v_mfma_f32_16x16x16_bf16 v[164:167], v[126:127], v[158:159], v[164:167]
	v_fma_f32 v108, v124, v108, v104
	v_fma_f32 v109, v125, v109, v105
	v_pk_fma_f32 v[106:107], v[100:101], v[106:107], v[142:143]
	v_pk_mul_f32 v[142:143], v[88:89], v[138:139]
	v_mfma_f32_16x16x16_bf16 v[150:153], v[132:133], v[158:159], v[150:153]
	v_mul_f32_e64 v138, v78, v138
	v_mul_f32_e64 v139, v79, v139
	v_pk_fma_f32 v[180:181], v[78:79], v[172:173], v[142:143] neg_lo:[0,0,1] neg_hi:[0,0,1]
	v_pk_fma_f32 v[172:173], v[88:89], v[172:173], v[138:139]
	v_mfma_f32_16x16x16_bf16 v[176:179], v[130:131], v[158:159], v[176:179]
	v_mul_f32_e64 v138, v94, v146
	v_mul_f32_e64 v139, v95, v147
	v_mfma_f32_16x16x16_bf16 v[104:107], v[136:137], v[158:159], v[106:109]
	s_nop 2
	v_mul_f32_e64 v108, v118, v140
	v_mul_f32_e64 v109, v119, v141
	v_mfma_f32_16x16x16_bf16 v[168:171], v[134:135], v[158:159], v[168:171]
	v_fma_f32 v182, v80, v174, -v108
	v_fma_f32 v183, v81, v175, -v109
	v_pk_mul_f32 v[108:109], v[80:81], v[140:141]
	s_waitcnt lgkmcnt(0)
; #define LAS __attribute__((address_space(3)))
; #define S5_UPDATE(K, hre, him, xq) do { const v2u xb_ = (xq); \
;     _Pragma("unroll") for (int j = 0; j < 4; ++j) { const f32x4 cre_ = K.ar[j] * hre[j] - K.ai[j] * him[j], cim_ = K.ar[j] * him[j] + K.ai[j] * hre[j]; \
;         hre[j] = MFMA16K16(K.Bf[2 * j], xb_, cre_); him[j] = MFMA16K16(K.Bf[2 * j + 1], xb_, cim_); } } while (0)
; __device__ __forceinline__ void s5_prompt_task(const Args& a, const Ctx& C, int b, int g, v4u (&xv)[8]) {
;     ...
;     const int chunk = 16 * w + n;
;     f32x4 hre[4], him[4];
; #pragma unroll
;     for (int j = 0; j < 4; ++j) { hre[j] = (f32x4){0.f, 0.f, 0.f, 0.f}; him[j] = (f32x4){0.f, 0.f, 0.f, 0.f}; }
;     const LAS unsigned char* xsl = XS + chunk * 528 + q * 8;
;     for (int t = 0; t < 16; ++t) { const v2u xq = *(const LAS v2u*)(xsl + t * 32); S5_UPDATE(K, hre, him, xq); }
	v_mfma_f32_16x16x16_bf16 v[140:143], v[114:115], v[154:155], v[180:183]
	v_fma_f32 v174, v118, v174, v108
	v_fma_f32 v175, v119, v175, v109
	v_pk_mul_f32 v[108:109], v[120:121], v[148:149]
	v_pk_fma_f32 v[180:181], v[82:83], v[164:165], v[138:139] neg_lo:[0,0,1] neg_hi:[0,0,1]
	v_pk_mul_f32 v[138:139], v[82:83], v[146:147]
	v_mfma_f32_16x16x16_bf16 v[172:175], v[116:117], v[154:155], v[172:175]
	v_fma_f32 v182, v86, v166, -v108
	v_fma_f32 v183, v87, v167, -v109
	v_pk_mul_f32 v[108:109], v[86:87], v[148:149]
	v_pk_fma_f32 v[146:147], v[94:95], v[164:165], v[138:139]
	v_pk_mul_f32 v[138:139], v[98:99], v[150:151]
	v_pk_fma_f32 v[148:149], v[120:121], v[166:167], v[108:109]
	v_pk_mul_f32 v[108:109], v[122:123], v[152:153]
	v_pk_fma_f32 v[164:165], v[84:85], v[176:177], v[138:139] neg_lo:[0,0,1] neg_hi:[0,0,1]
	v_pk_mul_f32 v[138:139], v[84:85], v[150:151]
	v_pk_fma_f32 v[166:167], v[92:93], v[178:179], v[108:109] neg_lo:[0,0,1] neg_hi:[0,0,1]
	v_pk_mul_f32 v[108:109], v[92:93], v[152:153]
	v_pk_fma_f32 v[150:151], v[98:99], v[176:177], v[138:139]
	v_pk_mul_f32 v[138:139], v[100:101], v[104:105]
	v_mfma_f32_16x16x16_bf16 v[146:149], v[128:129], v[154:155], v[146:149]
	v_fma_f32 v152, v122, v178, v108
	v_fma_f32 v153, v123, v179, v109
	v_pk_mul_f32 v[108:109], v[124:125], v[106:107]
	v_pk_fma_f32 v[176:177], v[90:91], v[168:169], v[138:139] neg_lo:[0,0,1] neg_hi:[0,0,1]
	v_pk_mul_f32 v[138:139], v[96:97], v[106:107]
	v_pk_mul_f32 v[104:105], v[90:91], v[104:105]
	v_mfma_f32_16x16x16_bf16 v[180:183], v[126:127], v[154:155], v[180:183]
	v_fma_f32 v178, v96, v170, -v108
	v_fma_f32 v179, v97, v171, -v109
	v_pk_fma_f32 v[170:171], v[124:125], v[170:171], v[138:139]
	v_pk_fma_f32 v[168:169], v[100:101], v[168:169], v[104:105]
	v_pk_mul_f32 v[104:105], v[118:119], v[174:175]
	v_pk_mul_f32 v[138:139], v[88:89], v[172:173]
	v_mfma_f32_16x16x16_bf16 v[150:153], v[132:133], v[154:155], v[150:153]
	v_mfma_f32_16x16x16_bf16 v[106:109], v[134:135], v[154:155], v[176:179]
	s_nop 2
	v_fma_f32 v178, v80, v142, -v104
	v_fma_f32 v179, v81, v143, -v105
	v_pk_fma_f32 v[176:177], v[78:79], v[140:141], v[138:139] neg_lo:[0,0,1] neg_hi:[0,0,1]
	v_pk_mul_f32 v[104:105], v[80:81], v[174:175]
	v_pk_mul_f32 v[138:139], v[78:79], v[172:173]
	v_mfma_f32_16x16x16_bf16 v[164:167], v[130:131], v[154:155], v[164:167]
	v_fma_f32 v142, v118, v142, v104
	v_fma_f32 v143, v119, v143, v105
	v_pk_fma_f32 v[140:141], v[88:89], v[140:141], v[138:139]
	v_pk_mul_f32 v[104:105], v[120:121], v[148:149]
	v_mfma_f32_16x16x16_bf16 v[168:171], v[136:137], v[154:155], v[168:171]
	v_fma_f32 v186, v86, v182, -v104
	v_fma_f32 v187, v87, v183, -v105
	v_pk_mul_f32 v[104:105], v[86:87], v[148:149]
	v_mfma_f32_16x16x16_bf16 v[138:141], v[116:117], v[156:157], v[140:143]
	v_fma_f32 v148, v120, v182, v104
	v_fma_f32 v149, v121, v183, v105
	v_pk_mul_f32 v[104:105], v[122:123], v[152:153]
	v_pk_mul_f32 v[142:143], v[94:95], v[146:147]
	v_mfma_f32_16x16x16_bf16 v[174:177], v[114:115], v[156:157], v[176:179]
	v_fma_f32 v184, v82, v180, -v142
	v_fma_f32 v185, v83, v181, -v143
	v_pk_mul_f32 v[142:143], v[82:83], v[146:147]
	s_nop 0
	v_pk_fma_f32 v[146:147], v[94:95], v[180:181], v[142:143]
	v_pk_mul_f32 v[142:143], v[98:99], v[150:151]
	v_pk_fma_f32 v[180:181], v[92:93], v[166:167], v[104:105] neg_lo:[0,0,1] neg_hi:[0,0,1]
	v_pk_fma_f32 v[178:179], v[84:85], v[164:165], v[142:143] neg_lo:[0,0,1] neg_hi:[0,0,1]
	v_pk_mul_f32 v[104:105], v[92:93], v[152:153]
	v_pk_mul_f32 v[142:143], v[84:85], v[150:151]
	v_pk_fma_f32 v[166:167], v[122:123], v[166:167], v[104:105]
	v_pk_fma_f32 v[164:165], v[98:99], v[164:165], v[142:143]
	v_pk_mul_f32 v[104:105], v[124:125], v[170:171]
	v_pk_mul_f32 v[142:143], v[100:101], v[168:169]
	v_mfma_f32_16x16x16_bf16 v[152:155], v[130:131], v[156:157], v[178:181]
	s_nop 2
	v_fma_f32 v180, v96, v108, -v104
	v_fma_f32 v181, v97, v109, -v105
	v_pk_fma_f32 v[178:179], v[90:91], v[106:107], v[142:143] neg_lo:[0,0,1] neg_hi:[0,0,1]
	v_pk_mul_f32 v[104:105], v[96:97], v[170:171]
	v_pk_mul_f32 v[142:143], v[90:91], v[168:169]
	v_pk_fma_f32 v[108:109], v[124:125], v[108:109], v[104:105]
	v_pk_fma_f32 v[106:107], v[100:101], v[106:107], v[142:143]
	v_mfma_f32_16x16x16_bf16 v[184:187], v[126:127], v[156:157], v[184:187]
	v_mul_f32_e64 v142, v88, v138
	v_mul_f32_e64 v143, v89, v139
	v_pk_mul_f32 v[138:139], v[78:79], v[138:139]
	v_mfma_f32_16x16x16_bf16 v[146:149], v[128:129], v[156:157], v[146:149]
	v_mfma_f32_16x16x16_bf16 v[164:167], v[132:133], v[156:157], v[164:167]
	v_mfma_f32_16x16x16_bf16 v[170:173], v[134:135], v[156:157], v[178:181]
	v_mfma_f32_16x16x16_bf16 v[104:107], v[136:137], v[156:157], v[106:109]
	ds_read2_b64 v[156:159], v163 offset0:56 offset1:60
	s_nop 0
	v_pk_fma_f32 v[178:179], v[78:79], v[174:175], v[142:143] neg_lo:[0,0,1] neg_hi:[0,0,1]
	v_pk_fma_f32 v[174:175], v[88:89], v[174:175], v[138:139]
	v_pk_mul_f32 v[108:109], v[118:119], v[140:141]
	v_pk_mul_f32 v[138:139], v[94:95], v[146:147]
	v_pk_fma_f32 v[180:181], v[80:81], v[176:177], v[108:109] neg_lo:[0,0,1] neg_hi:[0,0,1]
	v_pk_mul_f32 v[108:109], v[80:81], v[140:141]
	s_nop 0
	v_pk_fma_f32 v[176:177], v[118:119], v[176:177], v[108:109]
	v_pk_mul_f32 v[108:109], v[120:121], v[148:149]
	s_waitcnt lgkmcnt(0)
; #define LAS __attribute__((address_space(3)))
; #define S5_UPDATE(K, hre, him, xq) do { const v2u xb_ = (xq); \
;     _Pragma("unroll") for (int j = 0; j < 4; ++j) { const f32x4 cre_ = K.ar[j] * hre[j] - K.ai[j] * him[j], cim_ = K.ar[j] * him[j] + K.ai[j] * hre[j]; \
;         hre[j] = MFMA16K16(K.Bf[2 * j], xb_, cre_); him[j] = MFMA16K16(K.Bf[2 * j + 1], xb_, cim_); } } while (0)
; __device__ __forceinline__ void s5_prompt_task(const Args& a, const Ctx& C, int b, int g, v4u (&xv)[8]) {
;     ...
;     for (int t = 0; t < 16; ++t) { const v2u xq = *(const LAS v2u*)(xsl + t * 32); S5_UPDATE(K, hre, him, xq); }
; #pragma unroll
;     for (int j = 0; j < 4; ++j) { LAS float* d = SH + chunk * 132 + 2 * (16 * j + 4 * q);
;         *(LAS f32x4*)d = (f32x4){hre[j][0], him[j][0], hre[j][1], him[j][1]}; *(LAS f32x4*)(d + 4) = (f32x4){hre[j][2], him[j][2], hre[j][3], him[j][3]}; }
;     v2u zq[4];
; #pragma unroll
;     for (int t = 0; t < 4; ++t) zq[t] = __builtin_nontemporal_load((const v2u*)(ZBg + (size_t)(16 * chunk + t) * 16 + 4 * q));
	v_mfma_f32_16x16x16_bf16 v[140:143], v[114:115], v[156:157], v[178:181]
	s_nop 2
	v_fma_f32 v180, v86, v186, -v108
	v_fma_f32 v181, v87, v187, -v109
	v_pk_fma_f32 v[178:179], v[82:83], v[184:185], v[138:139] neg_lo:[0,0,1] neg_hi:[0,0,1]
	v_pk_mul_f32 v[138:139], v[82:83], v[146:147]
	v_mfma_f32_16x16x16_bf16 v[174:177], v[116:117], v[156:157], v[174:177]
	v_mul_f32_e64 v108, v86, v148
	v_mul_f32_e64 v109, v87, v149
	v_mfma_f32_16x16x16_bf16 v[148:151], v[126:127], v[156:157], v[178:181]
	s_nop 2
	v_fma_f32 v178, v94, v184, v138
	v_fma_f32 v179, v95, v185, v139
	v_pk_mul_f32 v[138:139], v[98:99], v[164:165]
	v_pk_fma_f32 v[180:181], v[120:121], v[186:187], v[108:109]
	v_pk_mul_f32 v[108:109], v[122:123], v[166:167]
	v_pk_fma_f32 v[182:183], v[84:85], v[152:153], v[138:139] neg_lo:[0,0,1] neg_hi:[0,0,1]
	v_pk_mul_f32 v[138:139], v[84:85], v[164:165]
	v_mfma_f32_16x16x16_bf16 v[178:181], v[128:129], v[156:157], v[178:181]
	v_fma_f32 v184, v92, v154, -v108
	v_fma_f32 v185, v93, v155, -v109
	v_pk_mul_f32 v[108:109], v[92:93], v[166:167]
	v_pk_fma_f32 v[152:153], v[98:99], v[152:153], v[138:139]
	v_pk_mul_f32 v[138:139], v[100:101], v[104:105]
	v_mfma_f32_16x16x16_bf16 v[166:169], v[130:131], v[156:157], v[182:185]
	v_fma_f32 v154, v122, v154, v108
	v_fma_f32 v155, v123, v155, v109
	v_pk_mul_f32 v[108:109], v[124:125], v[106:107]
	v_pk_mul_f32 v[104:105], v[90:91], v[104:105]
	v_pk_fma_f32 v[182:183], v[90:91], v[170:171], v[138:139] neg_lo:[0,0,1] neg_hi:[0,0,1]
	v_pk_mul_f32 v[138:139], v[96:97], v[106:107]
	v_mfma_f32_16x16x16_bf16 v[152:155], v[132:133], v[156:157], v[152:155]
	v_fma_f32 v184, v96, v172, -v108
	v_fma_f32 v185, v97, v173, -v109
	v_pk_fma_f32 v[172:173], v[124:125], v[172:173], v[138:139]
	v_pk_mul_f32 v[138:139], v[88:89], v[174:175]
	v_mfma_f32_16x16x16_bf16 v[106:109], v[134:135], v[156:157], v[182:185]
	v_fma_f32 v170, v100, v170, v104
	v_fma_f32 v171, v101, v171, v105
	v_pk_mul_f32 v[104:105], v[118:119], v[176:177]
	v_pk_fma_f32 v[182:183], v[78:79], v[140:141], v[138:139] neg_lo:[0,0,1] neg_hi:[0,0,1]
	v_pk_mul_f32 v[78:79], v[78:79], v[174:175]
	v_mfma_f32_16x16x16_bf16 v[170:173], v[136:137], v[156:157], v[170:173]
	v_fma_f32 v184, v80, v142, -v104
	v_fma_f32 v185, v81, v143, -v105
	v_pk_fma_f32 v[78:79], v[88:89], v[140:141], v[78:79]
	v_pk_mul_f32 v[88:89], v[120:121], v[180:181]
	v_pk_mul_f32 v[104:105], v[94:95], v[178:179]
	v_pk_fma_f32 v[140:141], v[86:87], v[150:151], v[88:89] neg_lo:[0,0,1] neg_hi:[0,0,1]
	v_pk_fma_f32 v[138:139], v[82:83], v[148:149], v[104:105] neg_lo:[0,0,1] neg_hi:[0,0,1]
	v_pk_mul_f32 v[82:83], v[82:83], v[178:179]
	v_pk_mul_f32 v[80:81], v[80:81], v[176:177]
	v_pk_mul_f32 v[104:105], v[86:87], v[180:181]
	v_mfma_f32_16x16x16_bf16 v[86:89], v[126:127], v[158:159], v[138:141]
	v_fma_f32 v80, v118, v142, v80
	v_fma_f32 v81, v119, v143, v81
	s_nop 0
	v_pk_fma_f32 v[138:139], v[94:95], v[148:149], v[82:83]
	v_pk_mul_f32 v[82:83], v[122:123], v[154:155]
	v_pk_fma_f32 v[140:141], v[120:121], v[150:151], v[104:105]
	v_pk_mul_f32 v[94:95], v[98:99], v[152:153]
	v_pk_fma_f32 v[148:149], v[92:93], v[168:169], v[82:83] neg_lo:[0,0,1] neg_hi:[0,0,1]
	v_pk_mul_f32 v[82:83], v[92:93], v[154:155]
	v_pk_mul_f32 v[104:105], v[84:85], v[152:153]
	v_mfma_f32_16x16x16_bf16 v[182:185], v[114:115], v[158:159], v[182:185]
	v_fma_f32 v146, v84, v166, -v94
	v_fma_f32 v147, v85, v167, -v95
	v_pk_fma_f32 v[84:85], v[122:123], v[168:169], v[82:83]
	v_pk_fma_f32 v[82:83], v[98:99], v[166:167], v[104:105]
	v_mfma_f32_16x16x16_bf16 v[78:81], v[116:117], v[158:159], v[78:81]
	v_mul_f32_e64 v104, v100, v170
	v_mul_f32_e64 v105, v101, v171
	v_pk_mul_f32 v[98:99], v[124:125], v[172:173]
	v_mov_b32_e32 v102, v183
	v_mfma_f32_16x16x16_bf16 v[138:141], v[128:129], v[158:159], v[138:141]
	v_lshlrev_b32_e32 v152, 3, v162
	s_nop 1
	v_mov_b32_e32 v103, v79
	v_mov_b32_e32 v79, v80
	v_mfma_f32_16x16x16_bf16 v[92:95], v[130:131], v[158:159], v[146:149]
	v_mov_b32_e32 v80, v185
	v_mov_b32_e32 v153, v111
	s_nop 0
	v_pk_fma_f32 v[146:147], v[90:91], v[106:107], v[104:105] neg_lo:[0,0,1] neg_hi:[0,0,1]
	v_pk_mul_f32 v[104:105], v[96:97], v[172:173]
	v_pk_mul_f32 v[90:91], v[90:91], v[170:171]
	v_mfma_f32_16x16x16_bf16 v[82:85], v[132:133], v[158:159], v[82:85]
	v_fma_f32 v148, v96, v108, -v98
	v_fma_f32 v149, v97, v109, -v99
	v_pk_fma_f32 v[108:109], v[124:125], v[108:109], v[104:105]
	v_pk_fma_f32 v[106:107], v[100:101], v[106:107], v[90:91]
	v_mfma_f32_16x16x16_bf16 v[96:99], v[134:135], v[158:159], v[146:149]
	v_mov_b32_e32 v101, v78
	v_mov_b32_e32 v78, v184
	ds_write_b128 v3, v[78:81] offset:16
	v_mfma_f32_16x16x16_bf16 v[104:107], v[136:137], v[158:159], v[106:109]
	v_mov_b32_e32 v78, v86
	v_mov_b32_e32 v79, v138
	v_mov_b32_e32 v80, v87
	v_mov_b32_e32 v81, v139
	ds_write_b128 v3, v[78:81] offset:128
	v_mov_b32_e32 v78, v92
	v_mov_b32_e32 v79, v82
	v_mov_b32_e32 v80, v93
	v_mov_b32_e32 v81, v83
	ds_write_b128 v3, v[78:81] offset:256
	v_mov_b32_e32 v78, v96
	v_mov_b32_e32 v79, v104
	v_mov_b32_e32 v80, v97
	v_mov_b32_e32 v81, v105
	v_mov_b32_e32 v138, v88
	v_mov_b32_e32 v139, v140
	v_mov_b32_e32 v140, v89
	v_mov_b32_e32 v82, v94
	v_mov_b32_e32 v83, v84
	v_mov_b32_e32 v84, v95
	ds_write_b128 v3, v[78:81] offset:384
	v_lshl_add_u64 v[78:79], s[4:5], 0, v[110:111]
	s_mov_b64 s[4:5], 0xd400000
	v_mov_b32_e32 v110, v7
	v_mov_b32_e32 v100, v182
	ds_write_b128 v3, v[138:141] offset:144
	ds_write_b128 v3, v[82:85] offset:272
	v_mov_b32_e32 v104, v98
	v_mov_b32_e32 v105, v106
	v_mov_b32_e32 v106, v99
	v_lshl_add_u64 v[138:139], v[78:79], 0, s[4:5]
	v_lshlrev_b64 v[78:79], 5, v[110:111]
	v_or_b32_e32 v80, 1, v7
	v_mov_b32_e32 v81, v111
	v_or_b32_e32 v82, 2, v7
	v_mov_b32_e32 v83, v111
	v_or_b32_e32 v84, 3, v7
	v_mov_b32_e32 v85, v111
	ds_write_b128 v3, v[100:103]
	ds_write_b128 v3, v[104:107] offset:400
	v_lshl_add_u64 v[78:79], v[138:139], 0, v[78:79]
	v_lshlrev_b64 v[80:81], 5, v[80:81]
	v_lshlrev_b64 v[82:83], 5, v[82:83]
	v_lshlrev_b64 v[84:85], 5, v[84:85]
	v_lshl_add_u64 v[80:81], v[138:139], 0, v[80:81]
	v_lshl_add_u64 v[82:83], v[138:139], 0, v[82:83]
	v_lshl_add_u64 v[84:85], v[138:139], 0, v[84:85]
	global_load_dwordx2 v[226:227], v[78:79], off nt
	global_load_dwordx2 v[228:229], v[80:81], off nt
	global_load_dwordx2 v[230:231], v[82:83], off nt
	global_load_dwordx2 v[232:233], v[84:85], off nt
	v_lshl_add_u64 v[78:79], s[6:7], 0, v[152:153]
	v_add_co_u32_e32 v80, vcc, s2, v78
	s_waitcnt lgkmcnt(0)
; #define LAS __attribute__((address_space(3)))
; #define LDS_WAIT() asm volatile("s_waitcnt lgkmcnt(0)" ::: "memory")
; __device__ __forceinline__ void s5_prompt_task(const Args& a, const Ctx& C, int b, int g, v4u (&xv)[8]) {
;     ...
;     LDS_WAIT();
;     { const float* A16 = (const float*)(a.ws + WS_S5C + S5C_A16) + (size_t)g * 128; const float* A256 = (const float*)(a.ws + WS_S5C + S5C_A256) + (size_t)g * 128;
;       const float a16r = A16[2 * lane], a16i = A16[2 * lane + 1], a256r = A256[2 * lane], a256i = A256[2 * lane + 1];
;       v2f sv[16];
; #pragma unroll
;       for (int i = 0; i < 16; ++i) sv[i] = *(const LAS v2f*)(SH + (16 * w + i) * 132 + 2 * lane);
;       float tr = 0.f, ti = 0.f;
; #pragma unroll
;       for (int i = 0; i < 16; ++i) { const float nr = a16r * tr - a16i * ti + sv[i][0], ni = a16r * ti + a16i * tr + sv[i][1]; tr = nr; ti = ni; }
;       TW[w * 128 + 2 * lane] = tr; TW[w * 128 + 2 * lane + 1] = ti;
;       __syncthreads();
	s_mov_b32 s2, 0x2310000
	s_nop 0
	v_addc_co_u32_e32 v81, vcc, 0, v79, vcc
	v_add_co_u32_e32 v78, vcc, s2, v78
	v_add_u32_e32 v7, s8, v152
	s_nop 0
	v_addc_co_u32_e32 v79, vcc, 0, v79, vcc
	s_mul_i32 s4, s82, 0x2100
	v_add_u32_e32 v7, s4, v7
	v_add_u32_e32 v11, 0x800, v7
	ds_read2_b64 v[106:109], v7 offset1:66
	ds_read2_b64 v[102:105], v7 offset0:132 offset1:198
	ds_read2_b64 v[98:101], v11 offset0:8 offset1:74
	ds_read2_b64 v[94:97], v11 offset0:140 offset1:206
	v_add_u32_e32 v11, 0x1000, v7
	ds_read2_b64 v[90:93], v11 offset0:16 offset1:82
	ds_read2_b64 v[86:89], v11 offset0:148 offset1:214
	v_add_u32_e32 v11, 0x1800, v7
	ds_read2_b64 v[82:85], v11 offset0:24 offset1:90
	ds_read2_b64 v[78:81], v11 offset0:156 offset1:222
	s_lshl_b32 s4, s82, 9
	s_add_i32 s4, s4, 0
	s_mov_b32 s2, 0
	s_cmp_lt_u32 s84, 64
	s_waitcnt vmcnt(4)
	v_mov_b32_e32 v148, v234
	v_mov_b32_e32 v149, v235
	v_mov_b32_e32 v150, v236
	v_mov_b32_e32 v151, v237
	v_mul_f32_e32 v11, 0, v148
	v_mul_f32_e32 v155, 0, v149
	v_sub_f32_e32 v154, v11, v155
	v_fmac_f32_e32 v155, 0, v148
	s_waitcnt lgkmcnt(7)
	v_pk_add_f32 v[154:155], v[154:155], v[106:107]
	v_add_u32_e32 v11, s4, v152
	v_pk_mul_f32 v[156:157], v[148:149], v[154:155] op_sel:[1,1] op_sel_hi:[0,1]
	v_pk_fma_f32 v[158:159], v[148:149], v[154:155], v[156:157] op_sel_hi:[1,0,1]
	v_pk_fma_f32 v[156:157], v[148:149], v[154:155], v[156:157] op_sel_hi:[1,0,1] neg_lo:[0,0,1] neg_hi:[0,0,1]
	v_add_u32_e32 v11, 0x21000, v11
	v_mov_b32_e32 v157, v159
	v_pk_add_f32 v[156:157], v[108:109], v[156:157]
	v_mov_b32_e32 v152, v111
	v_pk_mul_f32 v[158:159], v[148:149], v[156:157] op_sel:[1,1] op_sel_hi:[0,1]
	v_pk_fma_f32 v[164:165], v[148:149], v[156:157], v[158:159] op_sel_hi:[1,0,1]
	v_pk_fma_f32 v[158:159], v[148:149], v[156:157], v[158:159] op_sel_hi:[1,0,1] neg_lo:[0,0,1] neg_hi:[0,0,1]
	s_nop 0
	v_mov_b32_e32 v159, v165
	s_waitcnt lgkmcnt(6)
	v_pk_add_f32 v[158:159], v[102:103], v[158:159]
	s_nop 0
	v_pk_mul_f32 v[164:165], v[148:149], v[158:159] op_sel:[1,1] op_sel_hi:[0,1]
	v_pk_fma_f32 v[166:167], v[148:149], v[158:159], v[164:165] op_sel_hi:[1,0,1]
	v_pk_fma_f32 v[164:165], v[148:149], v[158:159], v[164:165] op_sel_hi:[1,0,1] neg_lo:[0,0,1] neg_hi:[0,0,1]
	s_nop 0
	v_mov_b32_e32 v165, v167
	v_pk_add_f32 v[164:165], v[104:105], v[164:165]
	s_nop 0
	v_pk_mul_f32 v[166:167], v[148:149], v[164:165] op_sel:[1,1] op_sel_hi:[0,1]
	v_pk_fma_f32 v[168:169], v[148:149], v[164:165], v[166:167] op_sel_hi:[1,0,1]
	v_pk_fma_f32 v[166:167], v[148:149], v[164:165], v[166:167] op_sel_hi:[1,0,1] neg_lo:[0,0,1] neg_hi:[0,0,1]
	s_nop 0
	v_mov_b32_e32 v167, v169
	s_waitcnt lgkmcnt(5)
	v_pk_add_f32 v[166:167], v[98:99], v[166:167]
	s_nop 0
	v_pk_mul_f32 v[168:169], v[148:149], v[166:167] op_sel:[1,1] op_sel_hi:[0,1]
	v_pk_fma_f32 v[170:171], v[148:149], v[166:167], v[168:169] op_sel_hi:[1,0,1]
	v_pk_fma_f32 v[168:169], v[148:149], v[166:167], v[168:169] op_sel_hi:[1,0,1] neg_lo:[0,0,1] neg_hi:[0,0,1]
	s_nop 0
	v_mov_b32_e32 v169, v171
	v_pk_add_f32 v[168:169], v[100:101], v[168:169]
	s_nop 0
	v_pk_mul_f32 v[170:171], v[148:149], v[168:169] op_sel:[1,1] op_sel_hi:[0,1]
	v_pk_fma_f32 v[172:173], v[148:149], v[168:169], v[170:171] op_sel_hi:[1,0,1]
	v_pk_fma_f32 v[170:171], v[148:149], v[168:169], v[170:171] op_sel_hi:[1,0,1] neg_lo:[0,0,1] neg_hi:[0,0,1]
	s_nop 0
	v_mov_b32_e32 v171, v173
	s_waitcnt lgkmcnt(4)
	v_pk_add_f32 v[170:171], v[94:95], v[170:171]
	s_nop 0
	v_pk_mul_f32 v[172:173], v[148:149], v[170:171] op_sel:[1,1] op_sel_hi:[0,1]
	v_pk_fma_f32 v[174:175], v[148:149], v[170:171], v[172:173] op_sel_hi:[1,0,1]
	v_pk_fma_f32 v[172:173], v[148:149], v[170:171], v[172:173] op_sel_hi:[1,0,1] neg_lo:[0,0,1] neg_hi:[0,0,1]
	s_nop 0
	v_mov_b32_e32 v173, v175
	v_pk_add_f32 v[172:173], v[96:97], v[172:173]
	s_nop 0
	v_pk_mul_f32 v[174:175], v[148:149], v[172:173] op_sel:[1,1] op_sel_hi:[0,1]
	v_pk_fma_f32 v[176:177], v[148:149], v[172:173], v[174:175] op_sel_hi:[1,0,1]
	v_pk_fma_f32 v[174:175], v[148:149], v[172:173], v[174:175] op_sel_hi:[1,0,1] neg_lo:[0,0,1] neg_hi:[0,0,1]
	s_nop 0
	v_mov_b32_e32 v175, v177
	s_waitcnt lgkmcnt(3)
	v_pk_add_f32 v[174:175], v[90:91], v[174:175]
	s_nop 0
	v_pk_mul_f32 v[176:177], v[148:149], v[174:175] op_sel:[1,1] op_sel_hi:[0,1]
	v_pk_fma_f32 v[178:179], v[148:149], v[174:175], v[176:177] op_sel_hi:[1,0,1]
	v_pk_fma_f32 v[176:177], v[148:149], v[174:175], v[176:177] op_sel_hi:[1,0,1] neg_lo:[0,0,1] neg_hi:[0,0,1]
	s_nop 0
	v_mov_b32_e32 v177, v179
	v_pk_add_f32 v[176:177], v[92:93], v[176:177]
	s_nop 0
	v_pk_mul_f32 v[178:179], v[148:149], v[176:177] op_sel:[1,1] op_sel_hi:[0,1]
	v_pk_fma_f32 v[180:181], v[148:149], v[176:177], v[178:179] op_sel_hi:[1,0,1]
	v_pk_fma_f32 v[178:179], v[148:149], v[176:177], v[178:179] op_sel_hi:[1,0,1] neg_lo:[0,0,1] neg_hi:[0,0,1]
	s_nop 0
	v_mov_b32_e32 v179, v181
	s_waitcnt lgkmcnt(2)
	v_pk_add_f32 v[178:179], v[86:87], v[178:179]
	s_nop 0
	v_pk_mul_f32 v[180:181], v[148:149], v[178:179] op_sel:[1,1] op_sel_hi:[0,1]
	v_pk_fma_f32 v[182:183], v[148:149], v[178:179], v[180:181] op_sel_hi:[1,0,1]
	v_pk_fma_f32 v[180:181], v[148:149], v[178:179], v[180:181] op_sel_hi:[1,0,1] neg_lo:[0,0,1] neg_hi:[0,0,1]
	s_nop 0
	v_mov_b32_e32 v181, v183
	v_pk_add_f32 v[182:183], v[88:89], v[180:181]
	s_nop 0
	v_pk_mul_f32 v[180:181], v[148:149], v[182:183] op_sel:[1,1] op_sel_hi:[0,1]
	v_pk_fma_f32 v[184:185], v[148:149], v[182:183], v[180:181] op_sel_hi:[1,0,1]
	v_pk_fma_f32 v[180:181], v[148:149], v[182:183], v[180:181] op_sel_hi:[1,0,1] neg_lo:[0,0,1] neg_hi:[0,0,1]
	s_nop 0
	v_mov_b32_e32 v181, v185
	s_waitcnt lgkmcnt(1)
	v_pk_add_f32 v[184:185], v[82:83], v[180:181]
	s_nop 0
	v_pk_mul_f32 v[180:181], v[148:149], v[184:185] op_sel:[1,1] op_sel_hi:[0,1]
	v_pk_fma_f32 v[186:187], v[148:149], v[184:185], v[180:181] op_sel_hi:[1,0,1]
	v_pk_fma_f32 v[180:181], v[148:149], v[184:185], v[180:181] op_sel_hi:[1,0,1] neg_lo:[0,0,1] neg_hi:[0,0,1]
	s_nop 0
	v_mov_b32_e32 v181, v187
	v_pk_add_f32 v[186:187], v[84:85], v[180:181]
	s_nop 0
	v_pk_mul_f32 v[180:181], v[148:149], v[186:187] op_sel:[1,1] op_sel_hi:[0,1]
	v_pk_fma_f32 v[188:189], v[148:149], v[186:187], v[180:181] op_sel_hi:[1,0,1]
	v_pk_fma_f32 v[180:181], v[148:149], v[186:187], v[180:181] op_sel_hi:[1,0,1] neg_lo:[0,0,1] neg_hi:[0,0,1]
	s_nop 0
	v_mov_b32_e32 v181, v189
	s_waitcnt lgkmcnt(0)
	v_pk_add_f32 v[188:189], v[78:79], v[180:181]
	s_nop 0
	v_pk_mul_f32 v[180:181], v[148:149], v[188:189] op_sel:[1,1] op_sel_hi:[0,1]
	v_pk_fma_f32 v[198:199], v[148:149], v[188:189], v[180:181] op_sel_hi:[1,0,1]
	v_pk_fma_f32 v[180:181], v[148:149], v[188:189], v[180:181] op_sel_hi:[1,0,1] neg_lo:[0,0,1] neg_hi:[0,0,1]
	s_nop 0
	v_mov_b32_e32 v181, v199
	v_pk_add_f32 v[180:181], v[80:81], v[180:181]
	ds_write_b64 v11, v[180:181]
	s_waitcnt lgkmcnt(0)
	s_barrier
; __device__ __forceinline__ void s5_prompt_task(const Args& a, const Ctx& C, int b, int g, v4u (&xv)[8]) {
;     ...
;       float hr = 0.f, hi = 0.f;
;       for (int v = 0; v < w; ++v) { const float sr = TW[v * 128 + 2 * lane], si = TW[v * 128 + 2 * lane + 1];
;           const float nr = a256r * hr - a256i * hi + sr, ni = a256r * hi + a256i * hr + si; hr = nr; hi = ni; }
	s_cbranch_scc1 .LBB0_985
	s_add_i32 s4, s82, -1
	s_cmp_lt_u32 s4, 7
	v_mov_b32_e32 v160, v111
	v_mov_b32_e32 v152, v111
	s_cbranch_scc1 .LBB0_977
	v_lshl_add_u32 v11, v162, 3, 0
	s_and_b32 s2, s82, 0x3fffff8
	s_waitcnt vmcnt(4)
	v_pk_mov_b32 v[154:155], v[150:151], v[150:151] op_sel:[1,0]
	s_mov_b32 s4, 0
	v_add_u32_e32 v11, 0x21000, v11
	v_mov_b32_e32 v152, 0
	v_mov_b32_e32 v160, 0
